# v33 + K-loop LDS-DMA in SADDR form (16 v_lshl_add_u64 removed per iteration, 5 GEMMs)
# speedup vs baseline: 1.0078x; 1.0078x over previous
; #define PG8_STAGE(bufoff, gbase, voff) do { _Pragma("unroll") for (int _i = 0; _i < 2; ++_i) \
;         __builtin_amdgcn_global_load_lds((const unsigned*)((const char*)(gbase) + (voff)[_i]), (PG8_LAS unsigned*)(lds + (bufoff) + ldsw + _i * 8192), 16, 0, 0); } while (0)
; #define PG8_LDA(dst, b, h) do { _Pragma("unroll") for (int m = 0; m < 4; ++m) _Pragma("unroll") for (int k = 0; k < 2; ++k) dst[m][k] = *(const PG8_LAS bf16x8*)(lds + PG8_SA(b, h) + aoff + m * 2048 + k * 1024); } while (0)
; #define PG8_LDB(dst, b, h) do { _Pragma("unroll") for (int n = 0; n < 2; ++n) _Pragma("unroll") for (int k = 0; k < 2; ++k) dst[n][k] = *(const PG8_LAS bf16x8*)(lds + PG8_SB(b, h) + boff + n * 2048 + k * 1024); } while (0)
; #define PG8_MMA(ai, bj, At, Bt) do { __builtin_amdgcn_s_setprio(1); _Pragma("unroll") for (int m = 0; m < 4; ++m) _Pragma("unroll") for (int n = 0; n < 2; ++n) _Pragma("unroll") for (int k = 0; k < 2; ++k) \
;         acc[ai][bj][m][n] = __builtin_amdgcn_mfma_f32_16x16x32_bf16(Bt[n][k], At[m][k], acc[ai][bj][m][n], 0, 0, 0); __builtin_amdgcn_s_setprio(0); } while (0)
; #define PG8_WAIT_V(n) asm volatile("s_waitcnt vmcnt(" #n ")" ::: "memory")
; template <class Epi, class Sched, bool ALIGN_EPI = false, bool SP2 = false>
; __device__ __forceinline__ void gemm_phase(PG8_LAS unsigned char* lds, const Gemm g, const Sched& S, const Epi& E) {
;     ...
;             PG8_LDB(B0, 0, 0); PG8_LDB(B1, 0, 1); PG8_SCHED; PG8_LDA(At, 0, 0); PG8_STAGE(PG8_SA(1, 1), a1 + hstep, voffA);
;             PG8_WAIT_V(8); PG8_WAIT_L(0); PG8_BAR; PG8_MMA(0, 0, At, B0); PG8_MMA(0, 1, At, B1); PG8_BAR; PG8_SCHED;
;             PG8_LDA(At, 0, 1); PG8_STAGE(PG8_SB(0, 0), b2, voffB); PG8_STAGE(PG8_SB(0, 1), b2 + hstep, voffB); PG8_STAGE(PG8_SA(0, 0), a2, voffA);
;             PG8_WAIT_V(8); PG8_WAIT_L(0); PG8_BAR; PG8_MMA(1, 0, At, B0); PG8_MMA(1, 1, At, B1); PG8_BAR; PG8_SCHED;
;             PG8_LDB(B0, 1, 0); PG8_LDB(B1, 1, 1); PG8_SCHED; PG8_LDA(At, 1, 0); PG8_STAGE(PG8_SA(0, 1), a2 + hstep, voffA);
;             PG8_WAIT_V(8); PG8_WAIT_L(0); PG8_BAR; PG8_MMA(0, 0, At, B0); PG8_MMA(0, 1, At, B1); PG8_BAR; PG8_SCHED;
;             PG8_LDA(At, 1, 1); PG8_STAGE(PG8_SB(1, 0), b3, voffB); PG8_STAGE(PG8_SB(1, 1), b3 + hstep, voffB); PG8_STAGE(PG8_SA(1, 0), a3, voffA);
;             PG8_WAIT_V(8); PG8_WAIT_L(0); PG8_BAR; PG8_MMA(1, 0, At, B0); PG8_MMA(1, 1, At, B1); PG8_BAR; PG8_SCHED;
.LBB0_139:
	s_add_u32 s36, s30, 0xfff80080
	s_addc_u32 s37, s31, -1
	s_add_i32 s70, 0, 0x10000
	s_cmp_eq_u32 s69, 28
	s_cselect_b32 s39, s25, s37
	s_cselect_b32 s38, s45, s36
	v_add_u32_e32 v142, s70, v148
	s_cselect_b32 s37, s23, s68
	s_cselect_b32 s36, s66, s67
	s_add_i32 s75, 0, 0x14000
	ds_read_b128 v[152:155], v142
	ds_read_b128 v[166:169], v142 offset:1024
	ds_read_b128 v[170:173], v142 offset:2048
	ds_read_b128 v[174:177], v142 offset:3072
	v_add_u32_e32 v142, s75, v148
	ds_read_b128 v[178:181], v142
	ds_read_b128 v[182:185], v142 offset:1024
	ds_read_b128 v[186:189], v142 offset:2048
	ds_read_b128 v[190:193], v142 offset:3072
	s_add_u32 s98, s30, 0xfff80000
	s_addc_u32 s99, s31, -1
	s_mov_b32 m0, s57
	s_nop 0
	global_load_lds_dwordx4 v138, s[98:99]
	s_mov_b32 m0, s58
	s_nop 0
	global_load_lds_dwordx4 v140, s[98:99]
	s_add_i32 m0, s53, 0xc000
	ds_read_b128 v[200:203], v151
	ds_read_b128 v[204:207], v151 offset:1024
	ds_read_b128 v[208:211], v151 offset:2048
	ds_read_b128 v[212:215], v151 offset:3072
	ds_read_b128 v[216:219], v151 offset:4096
	ds_read_b128 v[220:223], v151 offset:5120
	ds_read_b128 v[224:227], v151 offset:6144
	ds_read_b128 v[228:231], v151 offset:7168
	global_load_lds_dwordx4 v138, s[30:31]
	s_add_i32 m0, s53, 0xe000
	s_nop 0
	global_load_lds_dwordx4 v140, s[30:31]
	s_waitcnt vmcnt(8)
	s_waitcnt lgkmcnt(0)
	s_barrier
	s_setprio 1
	s_waitcnt lgkmcnt(0)
	v_mfma_f32_16x16x32_bf16 v[126:129], v[152:155], v[200:203], v[126:129]
	v_mfma_f32_16x16x32_bf16 v[122:125], v[170:173], v[200:203], v[122:125]
	v_mfma_f32_16x16x32_bf16 v[110:113], v[152:155], v[208:211], v[110:113]
	v_mfma_f32_16x16x32_bf16 v[106:109], v[170:173], v[208:211], v[106:109]
	v_mfma_f32_16x16x32_bf16 v[94:97], v[152:155], v[216:219], v[94:97]
	v_mfma_f32_16x16x32_bf16 v[90:93], v[170:173], v[216:219], v[90:93]
	v_mfma_f32_16x16x32_bf16 v[78:81], v[152:155], v[224:227], v[78:81]
	v_mfma_f32_16x16x32_bf16 v[74:77], v[170:173], v[224:227], v[74:77]
	v_mfma_f32_16x16x32_bf16 v[126:129], v[166:169], v[204:207], v[126:129]
	v_mfma_f32_16x16x32_bf16 v[122:125], v[174:177], v[204:207], v[122:125]
	v_mfma_f32_16x16x32_bf16 v[110:113], v[166:169], v[212:215], v[110:113]
	v_mfma_f32_16x16x32_bf16 v[106:109], v[174:177], v[212:215], v[106:109]
	v_mfma_f32_16x16x32_bf16 v[94:97], v[166:169], v[220:223], v[94:97]
	v_mfma_f32_16x16x32_bf16 v[90:93], v[174:177], v[220:223], v[90:93]
	v_mfma_f32_16x16x32_bf16 v[78:81], v[166:169], v[228:231], v[78:81]
	v_mfma_f32_16x16x32_bf16 v[74:77], v[174:177], v[228:231], v[74:77]
	s_setprio 0
	s_setprio 1
	v_mfma_f32_16x16x32_bf16 v[118:121], v[178:181], v[200:203], v[118:121]
	v_mfma_f32_16x16x32_bf16 v[114:117], v[186:189], v[200:203], v[114:117]
	v_mfma_f32_16x16x32_bf16 v[102:105], v[178:181], v[208:211], v[102:105]
	v_mfma_f32_16x16x32_bf16 v[98:101], v[186:189], v[208:211], v[98:101]
	v_mfma_f32_16x16x32_bf16 v[86:89], v[178:181], v[216:219], v[86:89]
	v_mfma_f32_16x16x32_bf16 v[82:85], v[186:189], v[216:219], v[82:85]
	v_mfma_f32_16x16x32_bf16 v[70:73], v[178:181], v[224:227], v[70:73]
	v_mfma_f32_16x16x32_bf16 v[66:69], v[186:189], v[224:227], v[66:69]
	v_mfma_f32_16x16x32_bf16 v[118:121], v[182:185], v[204:207], v[118:121]
	v_mfma_f32_16x16x32_bf16 v[114:117], v[190:193], v[204:207], v[114:117]
	v_mfma_f32_16x16x32_bf16 v[102:105], v[182:185], v[212:215], v[102:105]
	v_mfma_f32_16x16x32_bf16 v[98:101], v[190:193], v[212:215], v[98:101]
	v_mfma_f32_16x16x32_bf16 v[86:89], v[182:185], v[220:223], v[86:89]
	v_mfma_f32_16x16x32_bf16 v[82:85], v[190:193], v[220:223], v[82:85]
	v_mfma_f32_16x16x32_bf16 v[70:73], v[182:185], v[228:231], v[70:73]
	v_mfma_f32_16x16x32_bf16 v[66:69], v[190:193], v[228:231], v[66:69]
	s_setprio 0
	s_barrier
	s_add_i32 s70, s70, s52
	s_mov_b32 m0, s70
	ds_read_b128 v[200:203], v151 offset:16384
	ds_read_b128 v[204:207], v151 offset:17408
	ds_read_b128 v[208:211], v151 offset:18432
	ds_read_b128 v[212:215], v151 offset:19456
	ds_read_b128 v[216:219], v151 offset:20480
	ds_read_b128 v[220:223], v151 offset:21504
	ds_read_b128 v[224:227], v151 offset:22528
	ds_read_b128 v[228:231], v151 offset:23552
	global_load_lds_dwordx4 v158, s[36:37]
	s_add_i32 m0, s70, 0x2000
	s_add_u32 s70, s36, 0x80000
	s_addc_u32 s71, s37, 0
	s_add_i32 s75, s75, s52
	global_load_lds_dwordx4 v134, s[36:37]
	s_mov_b32 m0, s75
	s_nop 0
	global_load_lds_dwordx4 v158, s[70:71]
	s_add_i32 m0, s75, 0x2000
	s_nop 0
	global_load_lds_dwordx4 v134, s[70:71]
	s_waitcnt vmcnt(6)
	s_waitcnt lgkmcnt(0)
	s_barrier
	s_setprio 1
	s_waitcnt lgkmcnt(0)
	v_mfma_f32_16x16x32_bf16 v[62:65], v[152:155], v[200:203], v[62:65]
	v_mfma_f32_16x16x32_bf16 v[58:61], v[170:173], v[200:203], v[58:61]
	v_mfma_f32_16x16x32_bf16 v[46:49], v[152:155], v[208:211], v[46:49]
	v_mfma_f32_16x16x32_bf16 v[42:45], v[170:173], v[208:211], v[42:45]
	v_mfma_f32_16x16x32_bf16 v[30:33], v[152:155], v[216:219], v[30:33]
	v_mfma_f32_16x16x32_bf16 v[26:29], v[170:173], v[216:219], v[26:29]
	v_mfma_f32_16x16x32_bf16 v[14:17], v[152:155], v[224:227], v[14:17]
	v_mfma_f32_16x16x32_bf16 v[10:13], v[170:173], v[224:227], v[10:13]
	v_mfma_f32_16x16x32_bf16 v[62:65], v[166:169], v[204:207], v[62:65]
	v_mfma_f32_16x16x32_bf16 v[58:61], v[174:177], v[204:207], v[58:61]
	v_mfma_f32_16x16x32_bf16 v[46:49], v[166:169], v[212:215], v[46:49]
	v_mfma_f32_16x16x32_bf16 v[42:45], v[174:177], v[212:215], v[42:45]
	v_mfma_f32_16x16x32_bf16 v[30:33], v[166:169], v[220:223], v[30:33]
	v_mfma_f32_16x16x32_bf16 v[26:29], v[174:177], v[220:223], v[26:29]
	v_mfma_f32_16x16x32_bf16 v[14:17], v[166:169], v[228:231], v[14:17]
	v_mfma_f32_16x16x32_bf16 v[10:13], v[174:177], v[228:231], v[10:13]
	s_setprio 0
	s_setprio 1
	v_mfma_f32_16x16x32_bf16 v[54:57], v[178:181], v[200:203], v[54:57]
	v_mfma_f32_16x16x32_bf16 v[50:53], v[186:189], v[200:203], v[50:53]
	v_mfma_f32_16x16x32_bf16 v[38:41], v[178:181], v[208:211], v[38:41]
	v_mfma_f32_16x16x32_bf16 v[34:37], v[186:189], v[208:211], v[34:37]
	v_mfma_f32_16x16x32_bf16 v[22:25], v[178:181], v[216:219], v[22:25]
	v_mfma_f32_16x16x32_bf16 v[18:21], v[186:189], v[216:219], v[18:21]
	v_mfma_f32_16x16x32_bf16 v[6:9], v[178:181], v[224:227], v[6:9]
	v_mfma_f32_16x16x32_bf16 v[2:5], v[186:189], v[224:227], v[2:5]
	v_mfma_f32_16x16x32_bf16 v[54:57], v[182:185], v[204:207], v[54:57]
	v_mfma_f32_16x16x32_bf16 v[50:53], v[190:193], v[204:207], v[50:53]
	v_mfma_f32_16x16x32_bf16 v[38:41], v[182:185], v[212:215], v[38:41]
	v_mfma_f32_16x16x32_bf16 v[34:37], v[190:193], v[212:215], v[34:37]
	v_mfma_f32_16x16x32_bf16 v[22:25], v[182:185], v[220:223], v[22:25]
	v_mfma_f32_16x16x32_bf16 v[18:21], v[190:193], v[220:223], v[18:21]
	v_mfma_f32_16x16x32_bf16 v[6:9], v[182:185], v[228:231], v[6:9]
	v_mfma_f32_16x16x32_bf16 v[2:5], v[190:193], v[228:231], v[2:5]
	s_setprio 0
	s_barrier
; #define PG8_STAGE(bufoff, gbase, voff) do { _Pragma("unroll") for (int _i = 0; _i < 2; ++_i) \
;         __builtin_amdgcn_global_load_lds((const unsigned*)((const char*)(gbase) + (voff)[_i]), (PG8_LAS unsigned*)(lds + (bufoff) + ldsw + _i * 8192), 16, 0, 0); } while (0)
; #define PG8_LDA(dst, b, h) do { _Pragma("unroll") for (int m = 0; m < 4; ++m) _Pragma("unroll") for (int k = 0; k < 2; ++k) dst[m][k] = *(const PG8_LAS bf16x8*)(lds + PG8_SA(b, h) + aoff + m * 2048 + k * 1024); } while (0)
; #define PG8_LDB(dst, b, h) do { _Pragma("unroll") for (int n = 0; n < 2; ++n) _Pragma("unroll") for (int k = 0; k < 2; ++k) dst[n][k] = *(const PG8_LAS bf16x8*)(lds + PG8_SB(b, h) + boff + n * 2048 + k * 1024); } while (0)
; #define PG8_MMA(ai, bj, At, Bt) do { __builtin_amdgcn_s_setprio(1); _Pragma("unroll") for (int m = 0; m < 4; ++m) _Pragma("unroll") for (int n = 0; n < 2; ++n) _Pragma("unroll") for (int k = 0; k < 2; ++k) \
;         acc[ai][bj][m][n] = __builtin_amdgcn_mfma_f32_16x16x32_bf16(Bt[n][k], At[m][k], acc[ai][bj][m][n], 0, 0, 0); __builtin_amdgcn_s_setprio(0); } while (0)
; #define PG8_WAIT_V(n) asm volatile("s_waitcnt vmcnt(" #n ")" ::: "memory")
; template <class Epi, class Sched, bool ALIGN_EPI = false, bool SP2 = false>
; __device__ __forceinline__ void gemm_phase(PG8_LAS unsigned char* lds, const Gemm g, const Sched& S, const Epi& E) {
;     ...
;             PG8_LDB(B0, 0, 0); PG8_LDB(B1, 0, 1); PG8_SCHED; PG8_LDA(At, 0, 0); PG8_STAGE(PG8_SA(1, 1), a1 + hstep, voffA);
;             PG8_WAIT_V(8); PG8_WAIT_L(0); PG8_BAR; PG8_MMA(0, 0, At, B0); PG8_MMA(0, 1, At, B1); PG8_BAR; PG8_SCHED;
;             PG8_LDA(At, 0, 1); PG8_STAGE(PG8_SB(0, 0), b2, voffB); PG8_STAGE(PG8_SB(0, 1), b2 + hstep, voffB); PG8_STAGE(PG8_SA(0, 0), a2, voffA);
;             PG8_WAIT_V(8); PG8_WAIT_L(0); PG8_BAR; PG8_MMA(1, 0, At, B0); PG8_MMA(1, 1, At, B1); PG8_BAR; PG8_SCHED;
;             PG8_LDB(B0, 1, 0); PG8_LDB(B1, 1, 1); PG8_SCHED; PG8_LDA(At, 1, 0); PG8_STAGE(PG8_SA(0, 1), a2 + hstep, voffA);
;             PG8_WAIT_V(8); PG8_WAIT_L(0); PG8_BAR; PG8_MMA(0, 0, At, B0); PG8_MMA(0, 1, At, B1); PG8_BAR; PG8_SCHED;
;             PG8_LDA(At, 1, 1); PG8_STAGE(PG8_SB(1, 0), b3, voffB); PG8_STAGE(PG8_SB(1, 1), b3 + hstep, voffB); PG8_STAGE(PG8_SA(1, 0), a3, voffA);
;             PG8_WAIT_V(8); PG8_WAIT_L(0); PG8_BAR; PG8_MMA(1, 0, At, B0); PG8_MMA(1, 1, At, B1); PG8_BAR; PG8_SCHED;
	s_add_i32 s70, 0, 0x18000
	v_add_u32_e32 v142, s70, v148
	s_add_i32 s71, 0, 0x1c000
	ds_read_b128 v[152:155], v142
	ds_read_b128 v[166:169], v142 offset:1024
	ds_read_b128 v[170:173], v142 offset:2048
	ds_read_b128 v[174:177], v142 offset:3072
	v_add_u32_e32 v142, s71, v148
	ds_read_b128 v[178:181], v142
	ds_read_b128 v[182:185], v142 offset:1024
	ds_read_b128 v[186:189], v142 offset:2048
	ds_read_b128 v[190:193], v142 offset:3072
	s_mov_b32 m0, s53
	s_nop 0
	global_load_lds_dwordx4 v130, s[38:39]
	s_mov_b32 m0, s54
	s_nop 0
	global_load_lds_dwordx4 v132, s[38:39]
	s_add_u32 s38, s38, 0x80000
	s_addc_u32 s39, s39, 0
	s_mov_b32 m0, s55
	ds_read_b128 v[200:203], v151 offset:32768
	ds_read_b128 v[204:207], v151 offset:33792
	ds_read_b128 v[208:211], v151 offset:34816
	ds_read_b128 v[212:215], v151 offset:35840
	ds_read_b128 v[216:219], v151 offset:36864
	ds_read_b128 v[220:223], v151 offset:37888
	ds_read_b128 v[224:227], v151 offset:38912
	ds_read_b128 v[228:231], v151 offset:39936
	global_load_lds_dwordx4 v130, s[38:39]
	s_mov_b32 m0, s56
	s_nop 0
	global_load_lds_dwordx4 v132, s[38:39]
	s_waitcnt vmcnt(8)
	s_waitcnt lgkmcnt(0)
	s_barrier
	s_setprio 1
	s_waitcnt lgkmcnt(0)
	v_mfma_f32_16x16x32_bf16 v[126:129], v[152:155], v[200:203], v[126:129]
	v_mfma_f32_16x16x32_bf16 v[122:125], v[170:173], v[200:203], v[122:125]
	v_mfma_f32_16x16x32_bf16 v[110:113], v[152:155], v[208:211], v[110:113]
	v_mfma_f32_16x16x32_bf16 v[106:109], v[170:173], v[208:211], v[106:109]
	v_mfma_f32_16x16x32_bf16 v[94:97], v[152:155], v[216:219], v[94:97]
	v_mfma_f32_16x16x32_bf16 v[90:93], v[170:173], v[216:219], v[90:93]
	v_mfma_f32_16x16x32_bf16 v[78:81], v[152:155], v[224:227], v[78:81]
	v_mfma_f32_16x16x32_bf16 v[74:77], v[170:173], v[224:227], v[74:77]
	v_mfma_f32_16x16x32_bf16 v[126:129], v[166:169], v[204:207], v[126:129]
	v_mfma_f32_16x16x32_bf16 v[122:125], v[174:177], v[204:207], v[122:125]
	v_mfma_f32_16x16x32_bf16 v[110:113], v[166:169], v[212:215], v[110:113]
	v_mfma_f32_16x16x32_bf16 v[106:109], v[174:177], v[212:215], v[106:109]
	v_mfma_f32_16x16x32_bf16 v[94:97], v[166:169], v[220:223], v[94:97]
	v_mfma_f32_16x16x32_bf16 v[90:93], v[174:177], v[220:223], v[90:93]
	v_mfma_f32_16x16x32_bf16 v[78:81], v[166:169], v[228:231], v[78:81]
	v_mfma_f32_16x16x32_bf16 v[74:77], v[174:177], v[228:231], v[74:77]
	s_setprio 0
	s_setprio 1
	v_mfma_f32_16x16x32_bf16 v[118:121], v[178:181], v[200:203], v[118:121]
	v_mfma_f32_16x16x32_bf16 v[114:117], v[186:189], v[200:203], v[114:117]
	v_mfma_f32_16x16x32_bf16 v[102:105], v[178:181], v[208:211], v[102:105]
	v_mfma_f32_16x16x32_bf16 v[98:101], v[186:189], v[208:211], v[98:101]
	v_mfma_f32_16x16x32_bf16 v[86:89], v[178:181], v[216:219], v[86:89]
	v_mfma_f32_16x16x32_bf16 v[82:85], v[186:189], v[216:219], v[82:85]
	v_mfma_f32_16x16x32_bf16 v[70:73], v[178:181], v[224:227], v[70:73]
	v_mfma_f32_16x16x32_bf16 v[66:69], v[186:189], v[224:227], v[66:69]
	v_mfma_f32_16x16x32_bf16 v[118:121], v[182:185], v[204:207], v[118:121]
	v_mfma_f32_16x16x32_bf16 v[114:117], v[190:193], v[204:207], v[114:117]
	v_mfma_f32_16x16x32_bf16 v[102:105], v[182:185], v[212:215], v[102:105]
	v_mfma_f32_16x16x32_bf16 v[98:101], v[190:193], v[212:215], v[98:101]
	v_mfma_f32_16x16x32_bf16 v[86:89], v[182:185], v[220:223], v[86:89]
	v_mfma_f32_16x16x32_bf16 v[82:85], v[190:193], v[220:223], v[82:85]
	v_mfma_f32_16x16x32_bf16 v[70:73], v[182:185], v[228:231], v[70:73]
	v_mfma_f32_16x16x32_bf16 v[66:69], v[190:193], v[228:231], v[66:69]
	s_setprio 0
	s_barrier
	s_add_i32 s38, s70, s52
	s_add_i32 m0, s38, 0xffffff80
	ds_read_b128 v[200:203], v151 offset:49152
	ds_read_b128 v[204:207], v151 offset:50176
	ds_read_b128 v[208:211], v151 offset:51200
	ds_read_b128 v[212:215], v151 offset:52224
	ds_read_b128 v[216:219], v151 offset:53248
	ds_read_b128 v[220:223], v151 offset:54272
	ds_read_b128 v[224:227], v151 offset:55296
	ds_read_b128 v[228:231], v151 offset:56320
	global_load_lds_dwordx4 v158, s[36:37] offset:128
	s_add_i32 m0, s38, 0x1f80
	s_add_i32 s38, s71, s52
	global_load_lds_dwordx4 v134, s[36:37] offset:128
	s_add_u32 s36, s36, 0x80080
	s_addc_u32 s37, s37, 0
	s_mov_b32 m0, s38
	s_nop 0
	global_load_lds_dwordx4 v158, s[36:37]
	s_add_i32 m0, s38, 0x2000
	s_nop 0
	global_load_lds_dwordx4 v134, s[36:37]
	s_waitcnt vmcnt(6)
	s_waitcnt lgkmcnt(0)
	s_barrier
	s_setprio 1
	s_waitcnt lgkmcnt(0)
	v_mfma_f32_16x16x32_bf16 v[62:65], v[152:155], v[200:203], v[62:65]
	v_mfma_f32_16x16x32_bf16 v[58:61], v[170:173], v[200:203], v[58:61]
	v_mfma_f32_16x16x32_bf16 v[46:49], v[152:155], v[208:211], v[46:49]
	v_mfma_f32_16x16x32_bf16 v[42:45], v[170:173], v[208:211], v[42:45]
	v_mfma_f32_16x16x32_bf16 v[30:33], v[152:155], v[216:219], v[30:33]
	v_mfma_f32_16x16x32_bf16 v[26:29], v[170:173], v[216:219], v[26:29]
	v_mfma_f32_16x16x32_bf16 v[14:17], v[152:155], v[224:227], v[14:17]
	v_mfma_f32_16x16x32_bf16 v[10:13], v[170:173], v[224:227], v[10:13]
	v_mfma_f32_16x16x32_bf16 v[62:65], v[166:169], v[204:207], v[62:65]
	v_mfma_f32_16x16x32_bf16 v[58:61], v[174:177], v[204:207], v[58:61]
	v_mfma_f32_16x16x32_bf16 v[46:49], v[166:169], v[212:215], v[46:49]
	v_mfma_f32_16x16x32_bf16 v[42:45], v[174:177], v[212:215], v[42:45]
	v_mfma_f32_16x16x32_bf16 v[30:33], v[166:169], v[220:223], v[30:33]
	v_mfma_f32_16x16x32_bf16 v[26:29], v[174:177], v[220:223], v[26:29]
	v_mfma_f32_16x16x32_bf16 v[14:17], v[166:169], v[228:231], v[14:17]
	v_mfma_f32_16x16x32_bf16 v[10:13], v[174:177], v[228:231], v[10:13]
	s_setprio 0
	s_setprio 1
	v_mfma_f32_16x16x32_bf16 v[54:57], v[178:181], v[200:203], v[54:57]
	v_mfma_f32_16x16x32_bf16 v[50:53], v[186:189], v[200:203], v[50:53]
	v_mfma_f32_16x16x32_bf16 v[38:41], v[178:181], v[208:211], v[38:41]
	v_mfma_f32_16x16x32_bf16 v[34:37], v[186:189], v[208:211], v[34:37]
	v_mfma_f32_16x16x32_bf16 v[22:25], v[178:181], v[216:219], v[22:25]
	v_mfma_f32_16x16x32_bf16 v[18:21], v[186:189], v[216:219], v[18:21]
	v_mfma_f32_16x16x32_bf16 v[6:9], v[178:181], v[224:227], v[6:9]
	v_mfma_f32_16x16x32_bf16 v[2:5], v[186:189], v[224:227], v[2:5]
	v_mfma_f32_16x16x32_bf16 v[54:57], v[182:185], v[204:207], v[54:57]
	v_mfma_f32_16x16x32_bf16 v[50:53], v[190:193], v[204:207], v[50:53]
	v_mfma_f32_16x16x32_bf16 v[38:41], v[182:185], v[212:215], v[38:41]
	v_mfma_f32_16x16x32_bf16 v[34:37], v[190:193], v[212:215], v[34:37]
	v_mfma_f32_16x16x32_bf16 v[22:25], v[182:185], v[220:223], v[22:25]
	v_mfma_f32_16x16x32_bf16 v[18:21], v[190:193], v[220:223], v[18:21]
	v_mfma_f32_16x16x32_bf16 v[6:9], v[182:185], v[228:231], v[6:9]
	v_mfma_f32_16x16x32_bf16 v[2:5], v[190:193], v[228:231], v[2:5]
	s_setprio 0
	s_barrier
	s_add_i32 s69, s69, 2
	s_add_u32 s30, s30, 0x100
	s_addc_u32 s31, s31, 0
	s_add_u32 s67, s67, 0x100
	s_addc_u32 s68, s68, 0
	s_cmp_gt_u32 s69, 29
	s_cbranch_scc0 .LBB0_139
	s_and_b64 vcc, exec, s[16:17]
	s_cbranch_vccz .LBB0_142
	s_barrier

; #define PG8_STAGE(bufoff, gbase, voff) do { _Pragma("unroll") for (int _i = 0; _i < 2; ++_i) \
;         __builtin_amdgcn_global_load_lds((const unsigned*)((const char*)(gbase) + (voff)[_i]), (PG8_LAS unsigned*)(lds + (bufoff) + ldsw + _i * 8192), 16, 0, 0); } while (0)
; #define PG8_LDA(dst, b, h) do { _Pragma("unroll") for (int m = 0; m < 4; ++m) _Pragma("unroll") for (int k = 0; k < 2; ++k) dst[m][k] = *(const PG8_LAS bf16x8*)(lds + PG8_SA(b, h) + aoff + m * 2048 + k * 1024); } while (0)
; #define PG8_LDB(dst, b, h) do { _Pragma("unroll") for (int n = 0; n < 2; ++n) _Pragma("unroll") for (int k = 0; k < 2; ++k) dst[n][k] = *(const PG8_LAS bf16x8*)(lds + PG8_SB(b, h) + boff + n * 2048 + k * 1024); } while (0)
; #define PG8_MMA(ai, bj, At, Bt) do { __builtin_amdgcn_s_setprio(1); _Pragma("unroll") for (int m = 0; m < 4; ++m) _Pragma("unroll") for (int n = 0; n < 2; ++n) _Pragma("unroll") for (int k = 0; k < 2; ++k) \
;         acc[ai][bj][m][n] = __builtin_amdgcn_mfma_f32_16x16x32_bf16(Bt[n][k], At[m][k], acc[ai][bj][m][n], 0, 0, 0); __builtin_amdgcn_s_setprio(0); } while (0)
; #define PG8_WAIT_V(n) asm volatile("s_waitcnt vmcnt(" #n ")" ::: "memory")
; template <class Epi, class Sched, bool ALIGN_EPI = false, bool SP2 = false>
; __device__ __forceinline__ void gemm_phase(PG8_LAS unsigned char* lds, const Gemm g, const Sched& S, const Epi& E) {
;     ...
;             PG8_LDB(B0, 0, 0); PG8_LDB(B1, 0, 1); PG8_SCHED; PG8_LDA(At, 0, 0); PG8_STAGE(PG8_SA(1, 1), a1 + hstep, voffA);
;             PG8_WAIT_V(8); PG8_WAIT_L(0); PG8_BAR; PG8_MMA(0, 0, At, B0); PG8_MMA(0, 1, At, B1); PG8_BAR; PG8_SCHED;
;             PG8_LDA(At, 0, 1); PG8_STAGE(PG8_SB(0, 0), b2, voffB); PG8_STAGE(PG8_SB(0, 1), b2 + hstep, voffB); PG8_STAGE(PG8_SA(0, 0), a2, voffA);
;             PG8_WAIT_V(8); PG8_WAIT_L(0); PG8_BAR; PG8_MMA(1, 0, At, B0); PG8_MMA(1, 1, At, B1); PG8_BAR; PG8_SCHED;
;             PG8_LDB(B0, 1, 0); PG8_LDB(B1, 1, 1); PG8_SCHED; PG8_LDA(At, 1, 0); PG8_STAGE(PG8_SA(0, 1), a2 + hstep, voffA);
;             PG8_WAIT_V(8); PG8_WAIT_L(0); PG8_BAR; PG8_MMA(0, 0, At, B0); PG8_MMA(0, 1, At, B1); PG8_BAR; PG8_SCHED;
;             PG8_LDA(At, 1, 1); PG8_STAGE(PG8_SB(1, 0), b3, voffB); PG8_STAGE(PG8_SB(1, 1), b3 + hstep, voffB); PG8_STAGE(PG8_SA(1, 0), a3, voffA);
;             PG8_WAIT_V(8); PG8_WAIT_L(0); PG8_BAR; PG8_MMA(1, 0, At, B0); PG8_MMA(1, 1, At, B1); PG8_BAR; PG8_SCHED;
.LBB0_667:
	s_add_u32 s30, s0, 0xfff80080
	s_addc_u32 s31, s1, -1
	s_add_i32 s66, 0, 0x10000
	s_cmp_eq_u32 s63, 28
	s_cselect_b32 s37, s23, s31
	s_cselect_b32 s36, s59, s30
	s_cselect_b32 s31, s19, s62
	s_cselect_b32 s30, s60, s61
	s_add_i32 s68, 0, 0x14000
	v_add_u32_e32 v142, s66, v199
	v_add_u32_e32 v162, s68, v199
	ds_read_b128 v[130:133], v142
	ds_read_b128 v[134:137], v142 offset:1024
	ds_read_b128 v[138:141], v142 offset:2048
	ds_read_b128 v[142:145], v142 offset:3072
	ds_read_b128 v[146:149], v162
	ds_read_b128 v[150:153], v162 offset:1024
	ds_read_b128 v[154:157], v162 offset:2048
	ds_read_b128 v[162:165], v162 offset:3072
	s_add_u32 s98, s0, 0xfff80000
	s_addc_u32 s99, s1, -1
	s_mov_b32 m0, s54
	s_nop 0
	global_load_lds_dwordx4 v172, s[98:99]
	s_mov_b32 m0, s55
	s_nop 0
	global_load_lds_dwordx4 v174, s[98:99]
	s_add_i32 m0, s48, 0xc000
	ds_read_b128 v[176:179], v201
	ds_read_b128 v[180:183], v201 offset:1024
	ds_read_b128 v[184:187], v201 offset:2048
	ds_read_b128 v[188:191], v201 offset:3072
	ds_read_b128 v[202:205], v201 offset:4096
	ds_read_b128 v[206:209], v201 offset:5120
	ds_read_b128 v[210:213], v201 offset:6144
	ds_read_b128 v[214:217], v201 offset:7168
	global_load_lds_dwordx4 v172, s[0:1]
	s_add_i32 m0, s48, 0xe000
	s_nop 0
	global_load_lds_dwordx4 v174, s[0:1]
	s_waitcnt vmcnt(8)
	s_waitcnt lgkmcnt(0)
	s_barrier
	s_setprio 1
	s_waitcnt lgkmcnt(0)
	v_mfma_f32_16x16x32_bf16 v[126:129], v[130:133], v[176:179], v[126:129]
	v_mfma_f32_16x16x32_bf16 v[122:125], v[138:141], v[176:179], v[122:125]
	v_mfma_f32_16x16x32_bf16 v[110:113], v[130:133], v[184:187], v[110:113]
	v_mfma_f32_16x16x32_bf16 v[106:109], v[138:141], v[184:187], v[106:109]
	v_mfma_f32_16x16x32_bf16 v[94:97], v[130:133], v[202:205], v[94:97]
	v_mfma_f32_16x16x32_bf16 v[90:93], v[138:141], v[202:205], v[90:93]
	v_mfma_f32_16x16x32_bf16 v[78:81], v[130:133], v[210:213], v[78:81]
	v_mfma_f32_16x16x32_bf16 v[74:77], v[138:141], v[210:213], v[74:77]
	v_mfma_f32_16x16x32_bf16 v[126:129], v[134:137], v[180:183], v[126:129]
	v_mfma_f32_16x16x32_bf16 v[122:125], v[142:145], v[180:183], v[122:125]
	v_mfma_f32_16x16x32_bf16 v[110:113], v[134:137], v[188:191], v[110:113]
	v_mfma_f32_16x16x32_bf16 v[106:109], v[142:145], v[188:191], v[106:109]
	v_mfma_f32_16x16x32_bf16 v[94:97], v[134:137], v[206:209], v[94:97]
	v_mfma_f32_16x16x32_bf16 v[90:93], v[142:145], v[206:209], v[90:93]
	v_mfma_f32_16x16x32_bf16 v[78:81], v[134:137], v[214:217], v[78:81]
	v_mfma_f32_16x16x32_bf16 v[74:77], v[142:145], v[214:217], v[74:77]
	s_setprio 0
	s_setprio 1
	v_mfma_f32_16x16x32_bf16 v[118:121], v[146:149], v[176:179], v[118:121]
	v_mfma_f32_16x16x32_bf16 v[114:117], v[154:157], v[176:179], v[114:117]
	v_mfma_f32_16x16x32_bf16 v[102:105], v[146:149], v[184:187], v[102:105]
	v_mfma_f32_16x16x32_bf16 v[98:101], v[154:157], v[184:187], v[98:101]
	v_mfma_f32_16x16x32_bf16 v[86:89], v[146:149], v[202:205], v[86:89]
	v_mfma_f32_16x16x32_bf16 v[82:85], v[154:157], v[202:205], v[82:85]
	v_mfma_f32_16x16x32_bf16 v[70:73], v[146:149], v[210:213], v[70:73]
	v_mfma_f32_16x16x32_bf16 v[66:69], v[154:157], v[210:213], v[66:69]
	v_mfma_f32_16x16x32_bf16 v[118:121], v[150:153], v[180:183], v[118:121]
	v_mfma_f32_16x16x32_bf16 v[114:117], v[162:165], v[180:183], v[114:117]
	v_mfma_f32_16x16x32_bf16 v[102:105], v[150:153], v[188:191], v[102:105]
	v_mfma_f32_16x16x32_bf16 v[98:101], v[162:165], v[188:191], v[98:101]
	v_mfma_f32_16x16x32_bf16 v[86:89], v[150:153], v[206:209], v[86:89]
	v_mfma_f32_16x16x32_bf16 v[82:85], v[162:165], v[206:209], v[82:85]
	v_mfma_f32_16x16x32_bf16 v[70:73], v[150:153], v[214:217], v[70:73]
	v_mfma_f32_16x16x32_bf16 v[66:69], v[162:165], v[214:217], v[66:69]
	s_setprio 0
	s_barrier
	s_add_i32 s66, s66, s47
	s_mov_b32 m0, s66
	ds_read_b128 v[176:179], v201 offset:16384
	ds_read_b128 v[180:183], v201 offset:17408
	ds_read_b128 v[184:187], v201 offset:18432
	ds_read_b128 v[188:191], v201 offset:19456
	ds_read_b128 v[202:205], v201 offset:20480
	ds_read_b128 v[206:209], v201 offset:21504
	ds_read_b128 v[210:213], v201 offset:22528
	ds_read_b128 v[214:217], v201 offset:23552
	global_load_lds_dwordx4 v158, s[30:31]
	s_add_i32 m0, s66, 0x2000
	s_add_u32 s66, s30, 0x80000
	s_addc_u32 s67, s31, 0
	s_add_i32 s68, s68, s47
	global_load_lds_dwordx4 v166, s[30:31]
	s_mov_b32 m0, s68
	s_nop 0
	global_load_lds_dwordx4 v158, s[66:67]
	s_add_i32 m0, s68, 0x2000
	s_nop 0
	global_load_lds_dwordx4 v166, s[66:67]
	s_waitcnt vmcnt(6)
	s_waitcnt lgkmcnt(0)
	s_barrier
	s_setprio 1
	s_waitcnt lgkmcnt(0)
	v_mfma_f32_16x16x32_bf16 v[62:65], v[130:133], v[176:179], v[62:65]
	v_mfma_f32_16x16x32_bf16 v[58:61], v[138:141], v[176:179], v[58:61]
	v_mfma_f32_16x16x32_bf16 v[46:49], v[130:133], v[184:187], v[46:49]
	v_mfma_f32_16x16x32_bf16 v[42:45], v[138:141], v[184:187], v[42:45]
	v_mfma_f32_16x16x32_bf16 v[30:33], v[130:133], v[202:205], v[30:33]
	v_mfma_f32_16x16x32_bf16 v[26:29], v[138:141], v[202:205], v[26:29]
	v_mfma_f32_16x16x32_bf16 v[14:17], v[130:133], v[210:213], v[14:17]
	v_mfma_f32_16x16x32_bf16 v[10:13], v[138:141], v[210:213], v[10:13]
	v_mfma_f32_16x16x32_bf16 v[62:65], v[134:137], v[180:183], v[62:65]
	v_mfma_f32_16x16x32_bf16 v[58:61], v[142:145], v[180:183], v[58:61]
	v_mfma_f32_16x16x32_bf16 v[46:49], v[134:137], v[188:191], v[46:49]
	v_mfma_f32_16x16x32_bf16 v[42:45], v[142:145], v[188:191], v[42:45]
	v_mfma_f32_16x16x32_bf16 v[30:33], v[134:137], v[206:209], v[30:33]
	v_mfma_f32_16x16x32_bf16 v[26:29], v[142:145], v[206:209], v[26:29]
	v_mfma_f32_16x16x32_bf16 v[14:17], v[134:137], v[214:217], v[14:17]
	v_mfma_f32_16x16x32_bf16 v[10:13], v[142:145], v[214:217], v[10:13]
	s_setprio 0
	s_setprio 1
	v_mfma_f32_16x16x32_bf16 v[54:57], v[146:149], v[176:179], v[54:57]
	v_mfma_f32_16x16x32_bf16 v[50:53], v[154:157], v[176:179], v[50:53]
	v_mfma_f32_16x16x32_bf16 v[38:41], v[146:149], v[184:187], v[38:41]
	v_mfma_f32_16x16x32_bf16 v[34:37], v[154:157], v[184:187], v[34:37]
	v_mfma_f32_16x16x32_bf16 v[22:25], v[146:149], v[202:205], v[22:25]
	v_mfma_f32_16x16x32_bf16 v[18:21], v[154:157], v[202:205], v[18:21]
	v_mfma_f32_16x16x32_bf16 v[6:9], v[146:149], v[210:213], v[6:9]
	v_mfma_f32_16x16x32_bf16 v[2:5], v[154:157], v[210:213], v[2:5]
	v_mfma_f32_16x16x32_bf16 v[54:57], v[150:153], v[180:183], v[54:57]
	v_mfma_f32_16x16x32_bf16 v[50:53], v[162:165], v[180:183], v[50:53]
	v_mfma_f32_16x16x32_bf16 v[38:41], v[150:153], v[188:191], v[38:41]
	v_mfma_f32_16x16x32_bf16 v[34:37], v[162:165], v[188:191], v[34:37]
	v_mfma_f32_16x16x32_bf16 v[22:25], v[150:153], v[206:209], v[22:25]
	v_mfma_f32_16x16x32_bf16 v[18:21], v[162:165], v[206:209], v[18:21]
	v_mfma_f32_16x16x32_bf16 v[6:9], v[150:153], v[214:217], v[6:9]
	v_mfma_f32_16x16x32_bf16 v[2:5], v[162:165], v[214:217], v[2:5]
	s_setprio 0
	s_barrier
; #define PG8_STAGE(bufoff, gbase, voff) do { _Pragma("unroll") for (int _i = 0; _i < 2; ++_i) \
;         __builtin_amdgcn_global_load_lds((const unsigned*)((const char*)(gbase) + (voff)[_i]), (PG8_LAS unsigned*)(lds + (bufoff) + ldsw + _i * 8192), 16, 0, 0); } while (0)
; #define PG8_LDA(dst, b, h) do { _Pragma("unroll") for (int m = 0; m < 4; ++m) _Pragma("unroll") for (int k = 0; k < 2; ++k) dst[m][k] = *(const PG8_LAS bf16x8*)(lds + PG8_SA(b, h) + aoff + m * 2048 + k * 1024); } while (0)
; #define PG8_LDB(dst, b, h) do { _Pragma("unroll") for (int n = 0; n < 2; ++n) _Pragma("unroll") for (int k = 0; k < 2; ++k) dst[n][k] = *(const PG8_LAS bf16x8*)(lds + PG8_SB(b, h) + boff + n * 2048 + k * 1024); } while (0)
; #define PG8_MMA(ai, bj, At, Bt) do { __builtin_amdgcn_s_setprio(1); _Pragma("unroll") for (int m = 0; m < 4; ++m) _Pragma("unroll") for (int n = 0; n < 2; ++n) _Pragma("unroll") for (int k = 0; k < 2; ++k) \
;         acc[ai][bj][m][n] = __builtin_amdgcn_mfma_f32_16x16x32_bf16(Bt[n][k], At[m][k], acc[ai][bj][m][n], 0, 0, 0); __builtin_amdgcn_s_setprio(0); } while (0)
; #define PG8_WAIT_V(n) asm volatile("s_waitcnt vmcnt(" #n ")" ::: "memory")
; template <class Epi, class Sched, bool ALIGN_EPI = false, bool SP2 = false>
; __device__ __forceinline__ void gemm_phase(PG8_LAS unsigned char* lds, const Gemm g, const Sched& S, const Epi& E) {
;     ...
;             PG8_LDB(B0, 0, 0); PG8_LDB(B1, 0, 1); PG8_SCHED; PG8_LDA(At, 0, 0); PG8_STAGE(PG8_SA(1, 1), a1 + hstep, voffA);
;             PG8_WAIT_V(8); PG8_WAIT_L(0); PG8_BAR; PG8_MMA(0, 0, At, B0); PG8_MMA(0, 1, At, B1); PG8_BAR; PG8_SCHED;
;             PG8_LDA(At, 0, 1); PG8_STAGE(PG8_SB(0, 0), b2, voffB); PG8_STAGE(PG8_SB(0, 1), b2 + hstep, voffB); PG8_STAGE(PG8_SA(0, 0), a2, voffA);
;             PG8_WAIT_V(8); PG8_WAIT_L(0); PG8_BAR; PG8_MMA(1, 0, At, B0); PG8_MMA(1, 1, At, B1); PG8_BAR; PG8_SCHED;
;             PG8_LDB(B0, 1, 0); PG8_LDB(B1, 1, 1); PG8_SCHED; PG8_LDA(At, 1, 0); PG8_STAGE(PG8_SA(0, 1), a2 + hstep, voffA);
;             PG8_WAIT_V(8); PG8_WAIT_L(0); PG8_BAR; PG8_MMA(0, 0, At, B0); PG8_MMA(0, 1, At, B1); PG8_BAR; PG8_SCHED;
;             PG8_LDA(At, 1, 1); PG8_STAGE(PG8_SB(1, 0), b3, voffB); PG8_STAGE(PG8_SB(1, 1), b3 + hstep, voffB); PG8_STAGE(PG8_SA(1, 0), a3, voffA);
;             PG8_WAIT_V(8); PG8_WAIT_L(0); PG8_BAR; PG8_MMA(1, 0, At, B0); PG8_MMA(1, 1, At, B1); PG8_BAR; PG8_SCHED;
	s_add_i32 s66, 0, 0x18000
	s_add_i32 s67, 0, 0x1c000
	v_add_u32_e32 v142, s66, v199
	v_add_u32_e32 v162, s67, v199
	ds_read_b128 v[130:133], v142
	ds_read_b128 v[134:137], v142 offset:1024
	ds_read_b128 v[138:141], v142 offset:2048
	ds_read_b128 v[142:145], v142 offset:3072
	ds_read_b128 v[146:149], v162
	ds_read_b128 v[150:153], v162 offset:1024
	ds_read_b128 v[154:157], v162 offset:2048
	ds_read_b128 v[162:165], v162 offset:3072
	s_mov_b32 m0, s48
	s_nop 0
	global_load_lds_dwordx4 v170, s[36:37]
	s_mov_b32 m0, s49
	s_nop 0
	global_load_lds_dwordx4 v168, s[36:37]
	s_add_u32 s36, s36, 0x80000
	s_addc_u32 s37, s37, 0
	s_mov_b32 m0, s50
	ds_read_b128 v[176:179], v201 offset:32768
	ds_read_b128 v[180:183], v201 offset:33792
	ds_read_b128 v[184:187], v201 offset:34816
	ds_read_b128 v[188:191], v201 offset:35840
	ds_read_b128 v[202:205], v201 offset:36864
	ds_read_b128 v[206:209], v201 offset:37888
	ds_read_b128 v[210:213], v201 offset:38912
	ds_read_b128 v[214:217], v201 offset:39936
	global_load_lds_dwordx4 v170, s[36:37]
	s_mov_b32 m0, s51
	s_nop 0
	global_load_lds_dwordx4 v168, s[36:37]
	s_waitcnt vmcnt(8)
	s_waitcnt lgkmcnt(0)
	s_barrier
	s_setprio 1
	s_waitcnt lgkmcnt(0)
	v_mfma_f32_16x16x32_bf16 v[126:129], v[130:133], v[176:179], v[126:129]
	v_mfma_f32_16x16x32_bf16 v[122:125], v[138:141], v[176:179], v[122:125]
	v_mfma_f32_16x16x32_bf16 v[110:113], v[130:133], v[184:187], v[110:113]
	v_mfma_f32_16x16x32_bf16 v[106:109], v[138:141], v[184:187], v[106:109]
	v_mfma_f32_16x16x32_bf16 v[94:97], v[130:133], v[202:205], v[94:97]
	v_mfma_f32_16x16x32_bf16 v[90:93], v[138:141], v[202:205], v[90:93]
	v_mfma_f32_16x16x32_bf16 v[78:81], v[130:133], v[210:213], v[78:81]
	v_mfma_f32_16x16x32_bf16 v[74:77], v[138:141], v[210:213], v[74:77]
	v_mfma_f32_16x16x32_bf16 v[126:129], v[134:137], v[180:183], v[126:129]
	v_mfma_f32_16x16x32_bf16 v[122:125], v[142:145], v[180:183], v[122:125]
	v_mfma_f32_16x16x32_bf16 v[110:113], v[134:137], v[188:191], v[110:113]
	v_mfma_f32_16x16x32_bf16 v[106:109], v[142:145], v[188:191], v[106:109]
	v_mfma_f32_16x16x32_bf16 v[94:97], v[134:137], v[206:209], v[94:97]
	v_mfma_f32_16x16x32_bf16 v[90:93], v[142:145], v[206:209], v[90:93]
	v_mfma_f32_16x16x32_bf16 v[78:81], v[134:137], v[214:217], v[78:81]
	v_mfma_f32_16x16x32_bf16 v[74:77], v[142:145], v[214:217], v[74:77]
	s_setprio 0
	s_setprio 1
	v_mfma_f32_16x16x32_bf16 v[118:121], v[146:149], v[176:179], v[118:121]
	v_mfma_f32_16x16x32_bf16 v[114:117], v[154:157], v[176:179], v[114:117]
	v_mfma_f32_16x16x32_bf16 v[102:105], v[146:149], v[184:187], v[102:105]
	v_mfma_f32_16x16x32_bf16 v[98:101], v[154:157], v[184:187], v[98:101]
	v_mfma_f32_16x16x32_bf16 v[86:89], v[146:149], v[202:205], v[86:89]
	v_mfma_f32_16x16x32_bf16 v[82:85], v[154:157], v[202:205], v[82:85]
	v_mfma_f32_16x16x32_bf16 v[70:73], v[146:149], v[210:213], v[70:73]
	v_mfma_f32_16x16x32_bf16 v[66:69], v[154:157], v[210:213], v[66:69]
	v_mfma_f32_16x16x32_bf16 v[118:121], v[150:153], v[180:183], v[118:121]
	v_mfma_f32_16x16x32_bf16 v[114:117], v[162:165], v[180:183], v[114:117]
	v_mfma_f32_16x16x32_bf16 v[102:105], v[150:153], v[188:191], v[102:105]
	v_mfma_f32_16x16x32_bf16 v[98:101], v[162:165], v[188:191], v[98:101]
	v_mfma_f32_16x16x32_bf16 v[86:89], v[150:153], v[206:209], v[86:89]
	v_mfma_f32_16x16x32_bf16 v[82:85], v[162:165], v[206:209], v[82:85]
	v_mfma_f32_16x16x32_bf16 v[70:73], v[150:153], v[214:217], v[70:73]
	v_mfma_f32_16x16x32_bf16 v[66:69], v[162:165], v[214:217], v[66:69]
	s_setprio 0
	s_barrier
	s_add_i32 s36, s66, s47
	s_add_i32 m0, s36, 0xffffff80
	ds_read_b128 v[176:179], v201 offset:49152
	ds_read_b128 v[180:183], v201 offset:50176
	ds_read_b128 v[184:187], v201 offset:51200
	ds_read_b128 v[188:191], v201 offset:52224
	ds_read_b128 v[202:205], v201 offset:53248
	ds_read_b128 v[206:209], v201 offset:54272
	ds_read_b128 v[210:213], v201 offset:55296
	ds_read_b128 v[214:217], v201 offset:56320
	global_load_lds_dwordx4 v158, s[30:31] offset:128
	s_add_i32 m0, s36, 0x1f80
	s_add_i32 s36, s67, s47
	global_load_lds_dwordx4 v166, s[30:31] offset:128
	s_add_u32 s30, s30, 0x80080
	s_addc_u32 s31, s31, 0
	s_mov_b32 m0, s36
	s_nop 0
	global_load_lds_dwordx4 v158, s[30:31]
	s_add_i32 m0, s36, 0x2000
	s_nop 0
	global_load_lds_dwordx4 v166, s[30:31]
	s_waitcnt vmcnt(6)
	s_waitcnt lgkmcnt(0)
	s_barrier
	s_setprio 1
	s_waitcnt lgkmcnt(0)
	v_mfma_f32_16x16x32_bf16 v[62:65], v[130:133], v[176:179], v[62:65]
	v_mfma_f32_16x16x32_bf16 v[58:61], v[138:141], v[176:179], v[58:61]
	v_mfma_f32_16x16x32_bf16 v[46:49], v[130:133], v[184:187], v[46:49]
	v_mfma_f32_16x16x32_bf16 v[42:45], v[138:141], v[184:187], v[42:45]
	v_mfma_f32_16x16x32_bf16 v[30:33], v[130:133], v[202:205], v[30:33]
	v_mfma_f32_16x16x32_bf16 v[26:29], v[138:141], v[202:205], v[26:29]
	v_mfma_f32_16x16x32_bf16 v[14:17], v[130:133], v[210:213], v[14:17]
	v_mfma_f32_16x16x32_bf16 v[10:13], v[138:141], v[210:213], v[10:13]
	v_mfma_f32_16x16x32_bf16 v[62:65], v[134:137], v[180:183], v[62:65]
	v_mfma_f32_16x16x32_bf16 v[58:61], v[142:145], v[180:183], v[58:61]
	v_mfma_f32_16x16x32_bf16 v[46:49], v[134:137], v[188:191], v[46:49]
	v_mfma_f32_16x16x32_bf16 v[42:45], v[142:145], v[188:191], v[42:45]
	v_mfma_f32_16x16x32_bf16 v[30:33], v[134:137], v[206:209], v[30:33]
	v_mfma_f32_16x16x32_bf16 v[26:29], v[142:145], v[206:209], v[26:29]
	v_mfma_f32_16x16x32_bf16 v[14:17], v[134:137], v[214:217], v[14:17]
	v_mfma_f32_16x16x32_bf16 v[10:13], v[142:145], v[214:217], v[10:13]
	s_setprio 0
	s_setprio 1
	v_mfma_f32_16x16x32_bf16 v[54:57], v[146:149], v[176:179], v[54:57]
	v_mfma_f32_16x16x32_bf16 v[50:53], v[154:157], v[176:179], v[50:53]
	v_mfma_f32_16x16x32_bf16 v[38:41], v[146:149], v[184:187], v[38:41]
	v_mfma_f32_16x16x32_bf16 v[34:37], v[154:157], v[184:187], v[34:37]
	v_mfma_f32_16x16x32_bf16 v[22:25], v[146:149], v[202:205], v[22:25]
	v_mfma_f32_16x16x32_bf16 v[18:21], v[154:157], v[202:205], v[18:21]
	v_mfma_f32_16x16x32_bf16 v[6:9], v[146:149], v[210:213], v[6:9]
	v_mfma_f32_16x16x32_bf16 v[2:5], v[154:157], v[210:213], v[2:5]
	v_mfma_f32_16x16x32_bf16 v[54:57], v[150:153], v[180:183], v[54:57]
	v_mfma_f32_16x16x32_bf16 v[50:53], v[162:165], v[180:183], v[50:53]
	v_mfma_f32_16x16x32_bf16 v[38:41], v[150:153], v[188:191], v[38:41]
	v_mfma_f32_16x16x32_bf16 v[34:37], v[162:165], v[188:191], v[34:37]
	v_mfma_f32_16x16x32_bf16 v[22:25], v[150:153], v[206:209], v[22:25]
	v_mfma_f32_16x16x32_bf16 v[18:21], v[162:165], v[206:209], v[18:21]
	v_mfma_f32_16x16x32_bf16 v[6:9], v[150:153], v[214:217], v[6:9]
	v_mfma_f32_16x16x32_bf16 v[2:5], v[162:165], v[214:217], v[2:5]
	s_setprio 0
	s_barrier
	s_add_i32 s63, s63, 2
	s_add_u32 s0, s0, 0x100
	s_addc_u32 s1, s1, 0
	s_add_u32 s61, s61, 0x100
	s_addc_u32 s62, s62, 0
	s_cmp_gt_u32 s63, 29
	s_cbranch_scc0 .LBB0_667
	s_and_b64 vcc, exec, s[16:17]
	s_cbranch_vccz .LBB0_670
	s_barrier

; #define PG8_STAGE(bufoff, gbase, voff) do { _Pragma("unroll") for (int _i = 0; _i < 2; ++_i) \
;         __builtin_amdgcn_global_load_lds((const unsigned*)((const char*)(gbase) + (voff)[_i]), (PG8_LAS unsigned*)(lds + (bufoff) + ldsw + _i * 8192), 16, 0, 0); } while (0)
; #define PG8_LDA(dst, b, h) do { _Pragma("unroll") for (int m = 0; m < 4; ++m) _Pragma("unroll") for (int k = 0; k < 2; ++k) dst[m][k] = *(const PG8_LAS bf16x8*)(lds + PG8_SA(b, h) + aoff + m * 2048 + k * 1024); } while (0)
; #define PG8_LDB(dst, b, h) do { _Pragma("unroll") for (int n = 0; n < 2; ++n) _Pragma("unroll") for (int k = 0; k < 2; ++k) dst[n][k] = *(const PG8_LAS bf16x8*)(lds + PG8_SB(b, h) + boff + n * 2048 + k * 1024); } while (0)
; #define PG8_MMA(ai, bj, At, Bt) do { __builtin_amdgcn_s_setprio(1); _Pragma("unroll") for (int m = 0; m < 4; ++m) _Pragma("unroll") for (int n = 0; n < 2; ++n) _Pragma("unroll") for (int k = 0; k < 2; ++k) \
;         acc[ai][bj][m][n] = __builtin_amdgcn_mfma_f32_16x16x32_bf16(Bt[n][k], At[m][k], acc[ai][bj][m][n], 0, 0, 0); __builtin_amdgcn_s_setprio(0); } while (0)
; #define PG8_WAIT_V(n) asm volatile("s_waitcnt vmcnt(" #n ")" ::: "memory")
; template <class Epi, class Sched, bool ALIGN_EPI = false, bool SP2 = false>
; __device__ __forceinline__ void gemm_phase(PG8_LAS unsigned char* lds, const Gemm g, const Sched& S, const Epi& E) {
;     ...
;             PG8_LDB(B0, 0, 0); PG8_LDB(B1, 0, 1); PG8_SCHED; PG8_LDA(At, 0, 0); PG8_STAGE(PG8_SA(1, 1), a1 + hstep, voffA);
;             PG8_WAIT_V(8); PG8_WAIT_L(0); PG8_BAR; PG8_MMA(0, 0, At, B0); PG8_MMA(0, 1, At, B1); PG8_BAR; PG8_SCHED;
;             PG8_LDA(At, 0, 1); PG8_STAGE(PG8_SB(0, 0), b2, voffB); PG8_STAGE(PG8_SB(0, 1), b2 + hstep, voffB); PG8_STAGE(PG8_SA(0, 0), a2, voffA);
;             PG8_WAIT_V(8); PG8_WAIT_L(0); PG8_BAR; PG8_MMA(1, 0, At, B0); PG8_MMA(1, 1, At, B1); PG8_BAR; PG8_SCHED;
;             PG8_LDB(B0, 1, 0); PG8_LDB(B1, 1, 1); PG8_SCHED; PG8_LDA(At, 1, 0); PG8_STAGE(PG8_SA(0, 1), a2 + hstep, voffA);
;             PG8_WAIT_V(8); PG8_WAIT_L(0); PG8_BAR; PG8_MMA(0, 0, At, B0); PG8_MMA(0, 1, At, B1); PG8_BAR; PG8_SCHED;
;             PG8_LDA(At, 1, 1); PG8_STAGE(PG8_SB(1, 0), b3, voffB); PG8_STAGE(PG8_SB(1, 1), b3 + hstep, voffB); PG8_STAGE(PG8_SA(1, 0), a3, voffA);
;             PG8_WAIT_V(8); PG8_WAIT_L(0); PG8_BAR; PG8_MMA(1, 0, At, B0); PG8_MMA(1, 1, At, B1); PG8_BAR; PG8_SCHED;
.LBB0_762:
	s_add_u32 s30, s0, 0xfff80080
	s_addc_u32 s31, s1, -1
	s_add_i32 s67, 0, 0x10000
	s_cmp_eq_u32 s66, 28
	s_cselect_b32 s37, s23, s31
	s_cselect_b32 s36, s60, s30
	v_add_u32_e32 v151, s67, v146
	s_cselect_b32 s31, s19, s63
	s_cselect_b32 s30, s61, s62
	s_add_i32 s70, 0, 0x14000
	ds_read_b128 v[140:143], v151
	ds_read_b128 v[152:155], v151 offset:1024
	ds_read_b128 v[162:165], v151 offset:2048
	ds_read_b128 v[166:169], v151 offset:3072
	v_add_u32_e32 v151, s70, v146
	ds_read_b128 v[170:173], v151
	ds_read_b128 v[174:177], v151 offset:1024
	ds_read_b128 v[178:181], v151 offset:2048
	ds_read_b128 v[182:185], v151 offset:3072
	s_add_u32 s98, s0, 0xfff80000
	s_addc_u32 s99, s1, -1
	s_mov_b32 m0, s52
	s_nop 0
	global_load_lds_dwordx4 v136, s[98:99]
	s_mov_b32 m0, s53
	s_nop 0
	global_load_lds_dwordx4 v138, s[98:99]
	s_add_i32 m0, s47, 0xc000
	ds_read_b128 v[186:189], v150
	ds_read_b128 v[190:193], v150 offset:1024
	ds_read_b128 v[200:203], v150 offset:2048
	ds_read_b128 v[204:207], v150 offset:3072
	ds_read_b128 v[208:211], v150 offset:4096
	ds_read_b128 v[212:215], v150 offset:5120
	ds_read_b128 v[216:219], v150 offset:6144
	ds_read_b128 v[220:223], v150 offset:7168
	global_load_lds_dwordx4 v136, s[0:1]
	s_add_i32 m0, s47, 0xe000
	s_nop 0
	global_load_lds_dwordx4 v138, s[0:1]
	s_waitcnt vmcnt(8)
	s_waitcnt lgkmcnt(0)
	s_barrier
	s_setprio 1
	s_waitcnt lgkmcnt(0)
	v_mfma_f32_16x16x32_bf16 v[126:129], v[140:143], v[186:189], v[126:129]
	v_mfma_f32_16x16x32_bf16 v[122:125], v[162:165], v[186:189], v[122:125]
	v_mfma_f32_16x16x32_bf16 v[110:113], v[140:143], v[200:203], v[110:113]
	v_mfma_f32_16x16x32_bf16 v[106:109], v[162:165], v[200:203], v[106:109]
	v_mfma_f32_16x16x32_bf16 v[94:97], v[140:143], v[208:211], v[94:97]
	v_mfma_f32_16x16x32_bf16 v[90:93], v[162:165], v[208:211], v[90:93]
	v_mfma_f32_16x16x32_bf16 v[78:81], v[140:143], v[216:219], v[78:81]
	v_mfma_f32_16x16x32_bf16 v[74:77], v[162:165], v[216:219], v[74:77]
	v_mfma_f32_16x16x32_bf16 v[126:129], v[152:155], v[190:193], v[126:129]
	v_mfma_f32_16x16x32_bf16 v[122:125], v[166:169], v[190:193], v[122:125]
	v_mfma_f32_16x16x32_bf16 v[110:113], v[152:155], v[204:207], v[110:113]
	v_mfma_f32_16x16x32_bf16 v[106:109], v[166:169], v[204:207], v[106:109]
	v_mfma_f32_16x16x32_bf16 v[94:97], v[152:155], v[212:215], v[94:97]
	v_mfma_f32_16x16x32_bf16 v[90:93], v[166:169], v[212:215], v[90:93]
	v_mfma_f32_16x16x32_bf16 v[78:81], v[152:155], v[220:223], v[78:81]
	v_mfma_f32_16x16x32_bf16 v[74:77], v[166:169], v[220:223], v[74:77]
	s_setprio 0
	s_setprio 1
	v_mfma_f32_16x16x32_bf16 v[118:121], v[170:173], v[186:189], v[118:121]
	v_mfma_f32_16x16x32_bf16 v[114:117], v[178:181], v[186:189], v[114:117]
	v_mfma_f32_16x16x32_bf16 v[102:105], v[170:173], v[200:203], v[102:105]
	v_mfma_f32_16x16x32_bf16 v[98:101], v[178:181], v[200:203], v[98:101]
	v_mfma_f32_16x16x32_bf16 v[86:89], v[170:173], v[208:211], v[86:89]
	v_mfma_f32_16x16x32_bf16 v[82:85], v[178:181], v[208:211], v[82:85]
	v_mfma_f32_16x16x32_bf16 v[70:73], v[170:173], v[216:219], v[70:73]
	v_mfma_f32_16x16x32_bf16 v[66:69], v[178:181], v[216:219], v[66:69]
	v_mfma_f32_16x16x32_bf16 v[118:121], v[174:177], v[190:193], v[118:121]
	v_mfma_f32_16x16x32_bf16 v[114:117], v[182:185], v[190:193], v[114:117]
	v_mfma_f32_16x16x32_bf16 v[102:105], v[174:177], v[204:207], v[102:105]
	v_mfma_f32_16x16x32_bf16 v[98:101], v[182:185], v[204:207], v[98:101]
	v_mfma_f32_16x16x32_bf16 v[86:89], v[174:177], v[212:215], v[86:89]
	v_mfma_f32_16x16x32_bf16 v[82:85], v[182:185], v[212:215], v[82:85]
	v_mfma_f32_16x16x32_bf16 v[70:73], v[174:177], v[220:223], v[70:73]
	v_mfma_f32_16x16x32_bf16 v[66:69], v[182:185], v[220:223], v[66:69]
	s_setprio 0
	s_barrier
	s_add_i32 s67, s67, s46
	s_mov_b32 m0, s67
	ds_read_b128 v[186:189], v150 offset:16384
	ds_read_b128 v[190:193], v150 offset:17408
	ds_read_b128 v[200:203], v150 offset:18432
	ds_read_b128 v[204:207], v150 offset:19456
	ds_read_b128 v[208:211], v150 offset:20480
	ds_read_b128 v[212:215], v150 offset:21504
	ds_read_b128 v[216:219], v150 offset:22528
	ds_read_b128 v[220:223], v150 offset:23552
	global_load_lds_dwordx4 v158, s[30:31]
	s_add_i32 m0, s67, 0x2000
	s_add_u32 s68, s30, 0x80000
	s_addc_u32 s69, s31, 0
	s_add_i32 s67, s70, s46
	global_load_lds_dwordx4 v134, s[30:31]
	s_mov_b32 m0, s67
	s_nop 0
	global_load_lds_dwordx4 v158, s[68:69]
	s_add_i32 m0, s67, 0x2000
	s_nop 0
	global_load_lds_dwordx4 v134, s[68:69]
	s_waitcnt vmcnt(6)
	s_waitcnt lgkmcnt(0)
	s_barrier
	s_setprio 1
	s_waitcnt lgkmcnt(0)
	v_mfma_f32_16x16x32_bf16 v[62:65], v[140:143], v[186:189], v[62:65]
	v_mfma_f32_16x16x32_bf16 v[58:61], v[162:165], v[186:189], v[58:61]
	v_mfma_f32_16x16x32_bf16 v[46:49], v[140:143], v[200:203], v[46:49]
	v_mfma_f32_16x16x32_bf16 v[42:45], v[162:165], v[200:203], v[42:45]
	v_mfma_f32_16x16x32_bf16 v[30:33], v[140:143], v[208:211], v[30:33]
	v_mfma_f32_16x16x32_bf16 v[26:29], v[162:165], v[208:211], v[26:29]
	v_mfma_f32_16x16x32_bf16 v[14:17], v[140:143], v[216:219], v[14:17]
	v_mfma_f32_16x16x32_bf16 v[10:13], v[162:165], v[216:219], v[10:13]
	v_mfma_f32_16x16x32_bf16 v[62:65], v[152:155], v[190:193], v[62:65]
	v_mfma_f32_16x16x32_bf16 v[58:61], v[166:169], v[190:193], v[58:61]
	v_mfma_f32_16x16x32_bf16 v[46:49], v[152:155], v[204:207], v[46:49]
	v_mfma_f32_16x16x32_bf16 v[42:45], v[166:169], v[204:207], v[42:45]
	v_mfma_f32_16x16x32_bf16 v[30:33], v[152:155], v[212:215], v[30:33]
	v_mfma_f32_16x16x32_bf16 v[26:29], v[166:169], v[212:215], v[26:29]
	v_mfma_f32_16x16x32_bf16 v[14:17], v[152:155], v[220:223], v[14:17]
	v_mfma_f32_16x16x32_bf16 v[10:13], v[166:169], v[220:223], v[10:13]
	s_setprio 0
	s_setprio 1
	v_mfma_f32_16x16x32_bf16 v[54:57], v[170:173], v[186:189], v[54:57]
	v_mfma_f32_16x16x32_bf16 v[50:53], v[178:181], v[186:189], v[50:53]
	v_mfma_f32_16x16x32_bf16 v[38:41], v[170:173], v[200:203], v[38:41]
	v_mfma_f32_16x16x32_bf16 v[34:37], v[178:181], v[200:203], v[34:37]
	v_mfma_f32_16x16x32_bf16 v[22:25], v[170:173], v[208:211], v[22:25]
	v_mfma_f32_16x16x32_bf16 v[18:21], v[178:181], v[208:211], v[18:21]
	v_mfma_f32_16x16x32_bf16 v[6:9], v[170:173], v[216:219], v[6:9]
	v_mfma_f32_16x16x32_bf16 v[2:5], v[178:181], v[216:219], v[2:5]
	v_mfma_f32_16x16x32_bf16 v[54:57], v[174:177], v[190:193], v[54:57]
	v_mfma_f32_16x16x32_bf16 v[50:53], v[182:185], v[190:193], v[50:53]
	v_mfma_f32_16x16x32_bf16 v[38:41], v[174:177], v[204:207], v[38:41]
	v_mfma_f32_16x16x32_bf16 v[34:37], v[182:185], v[204:207], v[34:37]
	v_mfma_f32_16x16x32_bf16 v[22:25], v[174:177], v[212:215], v[22:25]
	v_mfma_f32_16x16x32_bf16 v[18:21], v[182:185], v[212:215], v[18:21]
	v_mfma_f32_16x16x32_bf16 v[6:9], v[174:177], v[220:223], v[6:9]
	v_mfma_f32_16x16x32_bf16 v[2:5], v[182:185], v[220:223], v[2:5]
	s_setprio 0
	s_barrier
; #define PG8_STAGE(bufoff, gbase, voff) do { _Pragma("unroll") for (int _i = 0; _i < 2; ++_i) \
;         __builtin_amdgcn_global_load_lds((const unsigned*)((const char*)(gbase) + (voff)[_i]), (PG8_LAS unsigned*)(lds + (bufoff) + ldsw + _i * 8192), 16, 0, 0); } while (0)
; #define PG8_LDA(dst, b, h) do { _Pragma("unroll") for (int m = 0; m < 4; ++m) _Pragma("unroll") for (int k = 0; k < 2; ++k) dst[m][k] = *(const PG8_LAS bf16x8*)(lds + PG8_SA(b, h) + aoff + m * 2048 + k * 1024); } while (0)
; #define PG8_LDB(dst, b, h) do { _Pragma("unroll") for (int n = 0; n < 2; ++n) _Pragma("unroll") for (int k = 0; k < 2; ++k) dst[n][k] = *(const PG8_LAS bf16x8*)(lds + PG8_SB(b, h) + boff + n * 2048 + k * 1024); } while (0)
; #define PG8_MMA(ai, bj, At, Bt) do { __builtin_amdgcn_s_setprio(1); _Pragma("unroll") for (int m = 0; m < 4; ++m) _Pragma("unroll") for (int n = 0; n < 2; ++n) _Pragma("unroll") for (int k = 0; k < 2; ++k) \
;         acc[ai][bj][m][n] = __builtin_amdgcn_mfma_f32_16x16x32_bf16(Bt[n][k], At[m][k], acc[ai][bj][m][n], 0, 0, 0); __builtin_amdgcn_s_setprio(0); } while (0)
; #define PG8_WAIT_V(n) asm volatile("s_waitcnt vmcnt(" #n ")" ::: "memory")
; template <class Epi, class Sched, bool ALIGN_EPI = false, bool SP2 = false>
; __device__ __forceinline__ void gemm_phase(PG8_LAS unsigned char* lds, const Gemm g, const Sched& S, const Epi& E) {
;     ...
;             PG8_LDB(B0, 0, 0); PG8_LDB(B1, 0, 1); PG8_SCHED; PG8_LDA(At, 0, 0); PG8_STAGE(PG8_SA(1, 1), a1 + hstep, voffA);
;             PG8_WAIT_V(8); PG8_WAIT_L(0); PG8_BAR; PG8_MMA(0, 0, At, B0); PG8_MMA(0, 1, At, B1); PG8_BAR; PG8_SCHED;
;             PG8_LDA(At, 0, 1); PG8_STAGE(PG8_SB(0, 0), b2, voffB); PG8_STAGE(PG8_SB(0, 1), b2 + hstep, voffB); PG8_STAGE(PG8_SA(0, 0), a2, voffA);
;             PG8_WAIT_V(8); PG8_WAIT_L(0); PG8_BAR; PG8_MMA(1, 0, At, B0); PG8_MMA(1, 1, At, B1); PG8_BAR; PG8_SCHED;
;             PG8_LDB(B0, 1, 0); PG8_LDB(B1, 1, 1); PG8_SCHED; PG8_LDA(At, 1, 0); PG8_STAGE(PG8_SA(0, 1), a2 + hstep, voffA);
;             PG8_WAIT_V(8); PG8_WAIT_L(0); PG8_BAR; PG8_MMA(0, 0, At, B0); PG8_MMA(0, 1, At, B1); PG8_BAR; PG8_SCHED;
;             PG8_LDA(At, 1, 1); PG8_STAGE(PG8_SB(1, 0), b3, voffB); PG8_STAGE(PG8_SB(1, 1), b3 + hstep, voffB); PG8_STAGE(PG8_SA(1, 0), a3, voffA);
;             PG8_WAIT_V(8); PG8_WAIT_L(0); PG8_BAR; PG8_MMA(1, 0, At, B0); PG8_MMA(1, 1, At, B1); PG8_BAR; PG8_SCHED;
	s_add_i32 s67, 0, 0x18000
	v_add_u32_e32 v151, s67, v146
	s_add_i32 s68, 0, 0x1c000
	ds_read_b128 v[140:143], v151
	ds_read_b128 v[152:155], v151 offset:1024
	ds_read_b128 v[162:165], v151 offset:2048
	ds_read_b128 v[166:169], v151 offset:3072
	v_add_u32_e32 v151, s68, v146
	ds_read_b128 v[170:173], v151
	ds_read_b128 v[174:177], v151 offset:1024
	ds_read_b128 v[178:181], v151 offset:2048
	ds_read_b128 v[182:185], v151 offset:3072
	s_mov_b32 m0, s47
	s_nop 0
	global_load_lds_dwordx4 v130, s[36:37]
	s_mov_b32 m0, s48
	s_nop 0
	global_load_lds_dwordx4 v132, s[36:37]
	s_add_u32 s36, s36, 0x80000
	s_addc_u32 s37, s37, 0
	s_mov_b32 m0, s49
	ds_read_b128 v[186:189], v150 offset:32768
	ds_read_b128 v[190:193], v150 offset:33792
	ds_read_b128 v[200:203], v150 offset:34816
	ds_read_b128 v[204:207], v150 offset:35840
	ds_read_b128 v[208:211], v150 offset:36864
	ds_read_b128 v[212:215], v150 offset:37888
	ds_read_b128 v[216:219], v150 offset:38912
	ds_read_b128 v[220:223], v150 offset:39936
	global_load_lds_dwordx4 v130, s[36:37]
	s_mov_b32 m0, s50
	s_nop 0
	global_load_lds_dwordx4 v132, s[36:37]
	s_waitcnt vmcnt(8)
	s_waitcnt lgkmcnt(0)
	s_barrier
	s_setprio 1
	s_waitcnt lgkmcnt(0)
	v_mfma_f32_16x16x32_bf16 v[126:129], v[140:143], v[186:189], v[126:129]
	v_mfma_f32_16x16x32_bf16 v[122:125], v[162:165], v[186:189], v[122:125]
	v_mfma_f32_16x16x32_bf16 v[110:113], v[140:143], v[200:203], v[110:113]
	v_mfma_f32_16x16x32_bf16 v[106:109], v[162:165], v[200:203], v[106:109]
	v_mfma_f32_16x16x32_bf16 v[94:97], v[140:143], v[208:211], v[94:97]
	v_mfma_f32_16x16x32_bf16 v[90:93], v[162:165], v[208:211], v[90:93]
	v_mfma_f32_16x16x32_bf16 v[78:81], v[140:143], v[216:219], v[78:81]
	v_mfma_f32_16x16x32_bf16 v[74:77], v[162:165], v[216:219], v[74:77]
	v_mfma_f32_16x16x32_bf16 v[126:129], v[152:155], v[190:193], v[126:129]
	v_mfma_f32_16x16x32_bf16 v[122:125], v[166:169], v[190:193], v[122:125]
	v_mfma_f32_16x16x32_bf16 v[110:113], v[152:155], v[204:207], v[110:113]
	v_mfma_f32_16x16x32_bf16 v[106:109], v[166:169], v[204:207], v[106:109]
	v_mfma_f32_16x16x32_bf16 v[94:97], v[152:155], v[212:215], v[94:97]
	v_mfma_f32_16x16x32_bf16 v[90:93], v[166:169], v[212:215], v[90:93]
	v_mfma_f32_16x16x32_bf16 v[78:81], v[152:155], v[220:223], v[78:81]
	v_mfma_f32_16x16x32_bf16 v[74:77], v[166:169], v[220:223], v[74:77]
	s_setprio 0
	s_setprio 1
	v_mfma_f32_16x16x32_bf16 v[118:121], v[170:173], v[186:189], v[118:121]
	v_mfma_f32_16x16x32_bf16 v[114:117], v[178:181], v[186:189], v[114:117]
	v_mfma_f32_16x16x32_bf16 v[102:105], v[170:173], v[200:203], v[102:105]
	v_mfma_f32_16x16x32_bf16 v[98:101], v[178:181], v[200:203], v[98:101]
	v_mfma_f32_16x16x32_bf16 v[86:89], v[170:173], v[208:211], v[86:89]
	v_mfma_f32_16x16x32_bf16 v[82:85], v[178:181], v[208:211], v[82:85]
	v_mfma_f32_16x16x32_bf16 v[70:73], v[170:173], v[216:219], v[70:73]
	v_mfma_f32_16x16x32_bf16 v[66:69], v[178:181], v[216:219], v[66:69]
	v_mfma_f32_16x16x32_bf16 v[118:121], v[174:177], v[190:193], v[118:121]
	v_mfma_f32_16x16x32_bf16 v[114:117], v[182:185], v[190:193], v[114:117]
	v_mfma_f32_16x16x32_bf16 v[102:105], v[174:177], v[204:207], v[102:105]
	v_mfma_f32_16x16x32_bf16 v[98:101], v[182:185], v[204:207], v[98:101]
	v_mfma_f32_16x16x32_bf16 v[86:89], v[174:177], v[212:215], v[86:89]
	v_mfma_f32_16x16x32_bf16 v[82:85], v[182:185], v[212:215], v[82:85]
	v_mfma_f32_16x16x32_bf16 v[70:73], v[174:177], v[220:223], v[70:73]
	v_mfma_f32_16x16x32_bf16 v[66:69], v[182:185], v[220:223], v[66:69]
	s_setprio 0
	s_barrier
	s_add_i32 s36, s67, s46
	s_add_i32 m0, s36, 0xffffff80
	ds_read_b128 v[186:189], v150 offset:49152
	ds_read_b128 v[190:193], v150 offset:50176
	ds_read_b128 v[200:203], v150 offset:51200
	ds_read_b128 v[204:207], v150 offset:52224
	ds_read_b128 v[208:211], v150 offset:53248
	ds_read_b128 v[212:215], v150 offset:54272
	ds_read_b128 v[216:219], v150 offset:55296
	ds_read_b128 v[220:223], v150 offset:56320
	global_load_lds_dwordx4 v158, s[30:31] offset:128
	s_add_i32 m0, s36, 0x1f80
	s_add_i32 s36, s68, s46
	global_load_lds_dwordx4 v134, s[30:31] offset:128
	s_add_u32 s30, s30, 0x80080
	s_addc_u32 s31, s31, 0
	s_mov_b32 m0, s36
	s_nop 0
	global_load_lds_dwordx4 v158, s[30:31]
	s_add_i32 m0, s36, 0x2000
	s_nop 0
	global_load_lds_dwordx4 v134, s[30:31]
	s_waitcnt vmcnt(6)
	s_waitcnt lgkmcnt(0)
	s_barrier
	s_setprio 1
	s_waitcnt lgkmcnt(0)
	v_mfma_f32_16x16x32_bf16 v[62:65], v[140:143], v[186:189], v[62:65]
	v_mfma_f32_16x16x32_bf16 v[58:61], v[162:165], v[186:189], v[58:61]
	v_mfma_f32_16x16x32_bf16 v[46:49], v[140:143], v[200:203], v[46:49]
	v_mfma_f32_16x16x32_bf16 v[42:45], v[162:165], v[200:203], v[42:45]
	v_mfma_f32_16x16x32_bf16 v[30:33], v[140:143], v[208:211], v[30:33]
	v_mfma_f32_16x16x32_bf16 v[26:29], v[162:165], v[208:211], v[26:29]
	v_mfma_f32_16x16x32_bf16 v[14:17], v[140:143], v[216:219], v[14:17]
	v_mfma_f32_16x16x32_bf16 v[10:13], v[162:165], v[216:219], v[10:13]
	v_mfma_f32_16x16x32_bf16 v[62:65], v[152:155], v[190:193], v[62:65]
	v_mfma_f32_16x16x32_bf16 v[58:61], v[166:169], v[190:193], v[58:61]
	v_mfma_f32_16x16x32_bf16 v[46:49], v[152:155], v[204:207], v[46:49]
	v_mfma_f32_16x16x32_bf16 v[42:45], v[166:169], v[204:207], v[42:45]
	v_mfma_f32_16x16x32_bf16 v[30:33], v[152:155], v[212:215], v[30:33]
	v_mfma_f32_16x16x32_bf16 v[26:29], v[166:169], v[212:215], v[26:29]
	v_mfma_f32_16x16x32_bf16 v[14:17], v[152:155], v[220:223], v[14:17]
	v_mfma_f32_16x16x32_bf16 v[10:13], v[166:169], v[220:223], v[10:13]
	s_setprio 0
	s_setprio 1
	v_mfma_f32_16x16x32_bf16 v[54:57], v[170:173], v[186:189], v[54:57]
	v_mfma_f32_16x16x32_bf16 v[50:53], v[178:181], v[186:189], v[50:53]
	v_mfma_f32_16x16x32_bf16 v[38:41], v[170:173], v[200:203], v[38:41]
	v_mfma_f32_16x16x32_bf16 v[34:37], v[178:181], v[200:203], v[34:37]
	v_mfma_f32_16x16x32_bf16 v[22:25], v[170:173], v[208:211], v[22:25]
	v_mfma_f32_16x16x32_bf16 v[18:21], v[178:181], v[208:211], v[18:21]
	v_mfma_f32_16x16x32_bf16 v[6:9], v[170:173], v[216:219], v[6:9]
	v_mfma_f32_16x16x32_bf16 v[2:5], v[178:181], v[216:219], v[2:5]
	v_mfma_f32_16x16x32_bf16 v[54:57], v[174:177], v[190:193], v[54:57]
	v_mfma_f32_16x16x32_bf16 v[50:53], v[182:185], v[190:193], v[50:53]
	v_mfma_f32_16x16x32_bf16 v[38:41], v[174:177], v[204:207], v[38:41]
	v_mfma_f32_16x16x32_bf16 v[34:37], v[182:185], v[204:207], v[34:37]
	v_mfma_f32_16x16x32_bf16 v[22:25], v[174:177], v[212:215], v[22:25]
	v_mfma_f32_16x16x32_bf16 v[18:21], v[182:185], v[212:215], v[18:21]
	v_mfma_f32_16x16x32_bf16 v[6:9], v[174:177], v[220:223], v[6:9]
	v_mfma_f32_16x16x32_bf16 v[2:5], v[182:185], v[220:223], v[2:5]
	s_setprio 0
	s_barrier
	s_add_i32 s66, s66, 2
	s_add_u32 s0, s0, 0x100
	s_addc_u32 s1, s1, 0
	s_add_u32 s62, s62, 0x100
	s_addc_u32 s63, s63, 0
	s_cmp_gt_u32 s66, 29
	s_cbranch_scc0 .LBB0_762
	s_and_b64 vcc, exec, s[16:17]
	s_mov_b64 s[60:61], s[90:91]
	s_mov_b64 s[62:63], s[88:89]
	s_cbranch_vccz .LBB0_765
	s_barrier

; #define PG8_STAGE(bufoff, gbase, voff) do { _Pragma("unroll") for (int _i = 0; _i < 2; ++_i) \
;         __builtin_amdgcn_global_load_lds((const unsigned*)((const char*)(gbase) + (voff)[_i]), (PG8_LAS unsigned*)(lds + (bufoff) + ldsw + _i * 8192), 16, 0, 0); } while (0)
; #define PG8_LDA(dst, b, h) do { _Pragma("unroll") for (int m = 0; m < 4; ++m) _Pragma("unroll") for (int k = 0; k < 2; ++k) dst[m][k] = *(const PG8_LAS bf16x8*)(lds + PG8_SA(b, h) + aoff + m * 2048 + k * 1024); } while (0)
; #define PG8_LDB(dst, b, h) do { _Pragma("unroll") for (int n = 0; n < 2; ++n) _Pragma("unroll") for (int k = 0; k < 2; ++k) dst[n][k] = *(const PG8_LAS bf16x8*)(lds + PG8_SB(b, h) + boff + n * 2048 + k * 1024); } while (0)
; #define PG8_MMA(ai, bj, At, Bt) do { __builtin_amdgcn_s_setprio(1); _Pragma("unroll") for (int m = 0; m < 4; ++m) _Pragma("unroll") for (int n = 0; n < 2; ++n) _Pragma("unroll") for (int k = 0; k < 2; ++k) \
;         acc[ai][bj][m][n] = __builtin_amdgcn_mfma_f32_16x16x32_bf16(Bt[n][k], At[m][k], acc[ai][bj][m][n], 0, 0, 0); __builtin_amdgcn_s_setprio(0); } while (0)
; #define PG8_WAIT_V(n) asm volatile("s_waitcnt vmcnt(" #n ")" ::: "memory")
; template <class Epi, class Sched, bool ALIGN_EPI = false, bool SP2 = false>
; __device__ __forceinline__ void gemm_phase(PG8_LAS unsigned char* lds, const Gemm g, const Sched& S, const Epi& E) {
;     ...
;             PG8_LDB(B0, 0, 0); PG8_LDB(B1, 0, 1); PG8_SCHED; PG8_LDA(At, 0, 0); PG8_STAGE(PG8_SA(1, 1), a1 + hstep, voffA);
;             PG8_WAIT_V(8); PG8_WAIT_L(0); PG8_BAR; PG8_MMA(0, 0, At, B0); PG8_MMA(0, 1, At, B1); PG8_BAR; PG8_SCHED;
;             PG8_LDA(At, 0, 1); PG8_STAGE(PG8_SB(0, 0), b2, voffB); PG8_STAGE(PG8_SB(0, 1), b2 + hstep, voffB); PG8_STAGE(PG8_SA(0, 0), a2, voffA);
;             PG8_WAIT_V(8); PG8_WAIT_L(0); PG8_BAR; PG8_MMA(1, 0, At, B0); PG8_MMA(1, 1, At, B1); PG8_BAR; PG8_SCHED;
;             PG8_LDB(B0, 1, 0); PG8_LDB(B1, 1, 1); PG8_SCHED; PG8_LDA(At, 1, 0); PG8_STAGE(PG8_SA(0, 1), a2 + hstep, voffA);
;             PG8_WAIT_V(8); PG8_WAIT_L(0); PG8_BAR; PG8_MMA(0, 0, At, B0); PG8_MMA(0, 1, At, B1); PG8_BAR; PG8_SCHED;
;             PG8_LDA(At, 1, 1); PG8_STAGE(PG8_SB(1, 0), b3, voffB); PG8_STAGE(PG8_SB(1, 1), b3 + hstep, voffB); PG8_STAGE(PG8_SA(1, 0), a3, voffA);
;             PG8_WAIT_V(8); PG8_WAIT_L(0); PG8_BAR; PG8_MMA(1, 0, At, B0); PG8_MMA(1, 1, At, B1); PG8_BAR; PG8_SCHED;
.LBB0_842:
	s_add_u32 s30, s0, 0xffe00080
	s_addc_u32 s31, s1, -1
	s_add_i32 s68, 0, 0x10000
	s_cmpk_eq_i32 s67, 0x7c
	s_cselect_b32 s37, s23, s31
	s_cselect_b32 s36, s61, s30
	s_cselect_b32 s31, s19, s66
	s_cselect_b32 s30, s62, s63
	s_add_i32 s70, 0, 0x14000
	v_add_u32_e32 v142, s68, v199
	v_add_u32_e32 v162, s70, v199
	ds_read_b128 v[130:133], v142
	ds_read_b128 v[134:137], v142 offset:1024
	ds_read_b128 v[138:141], v142 offset:2048
	ds_read_b128 v[142:145], v142 offset:3072
	ds_read_b128 v[146:149], v162
	ds_read_b128 v[150:153], v162 offset:1024
	ds_read_b128 v[154:157], v162 offset:2048
	ds_read_b128 v[162:165], v162 offset:3072
	s_add_u32 s98, s0, 0xffe00000
	s_addc_u32 s99, s1, -1
	s_mov_b32 m0, s56
	s_nop 0
	global_load_lds_dwordx4 v172, s[98:99]
	s_mov_b32 m0, s57
	s_nop 0
	global_load_lds_dwordx4 v174, s[98:99]
	s_add_i32 m0, s51, 0xc000
	ds_read_b128 v[176:179], v201
	ds_read_b128 v[180:183], v201 offset:1024
	ds_read_b128 v[184:187], v201 offset:2048
	ds_read_b128 v[188:191], v201 offset:3072
	ds_read_b128 v[202:205], v201 offset:4096
	ds_read_b128 v[206:209], v201 offset:5120
	ds_read_b128 v[210:213], v201 offset:6144
	ds_read_b128 v[214:217], v201 offset:7168
	global_load_lds_dwordx4 v172, s[0:1]
	s_add_i32 m0, s51, 0xe000
	s_nop 0
	global_load_lds_dwordx4 v174, s[0:1]
	s_waitcnt vmcnt(8)
	s_waitcnt lgkmcnt(0)
	s_barrier
	s_setprio 1
	s_waitcnt lgkmcnt(0)
	v_mfma_f32_16x16x32_bf16 v[126:129], v[130:133], v[176:179], v[126:129]
	v_mfma_f32_16x16x32_bf16 v[122:125], v[138:141], v[176:179], v[122:125]
	v_mfma_f32_16x16x32_bf16 v[110:113], v[130:133], v[184:187], v[110:113]
	v_mfma_f32_16x16x32_bf16 v[106:109], v[138:141], v[184:187], v[106:109]
	v_mfma_f32_16x16x32_bf16 v[94:97], v[130:133], v[202:205], v[94:97]
	v_mfma_f32_16x16x32_bf16 v[90:93], v[138:141], v[202:205], v[90:93]
	v_mfma_f32_16x16x32_bf16 v[78:81], v[130:133], v[210:213], v[78:81]
	v_mfma_f32_16x16x32_bf16 v[74:77], v[138:141], v[210:213], v[74:77]
	v_mfma_f32_16x16x32_bf16 v[126:129], v[134:137], v[180:183], v[126:129]
	v_mfma_f32_16x16x32_bf16 v[122:125], v[142:145], v[180:183], v[122:125]
	v_mfma_f32_16x16x32_bf16 v[110:113], v[134:137], v[188:191], v[110:113]
	v_mfma_f32_16x16x32_bf16 v[106:109], v[142:145], v[188:191], v[106:109]
	v_mfma_f32_16x16x32_bf16 v[94:97], v[134:137], v[206:209], v[94:97]
	v_mfma_f32_16x16x32_bf16 v[90:93], v[142:145], v[206:209], v[90:93]
	v_mfma_f32_16x16x32_bf16 v[78:81], v[134:137], v[214:217], v[78:81]
	v_mfma_f32_16x16x32_bf16 v[74:77], v[142:145], v[214:217], v[74:77]
	s_setprio 0
	s_setprio 1
	v_mfma_f32_16x16x32_bf16 v[118:121], v[146:149], v[176:179], v[118:121]
	v_mfma_f32_16x16x32_bf16 v[114:117], v[154:157], v[176:179], v[114:117]
	v_mfma_f32_16x16x32_bf16 v[102:105], v[146:149], v[184:187], v[102:105]
	v_mfma_f32_16x16x32_bf16 v[98:101], v[154:157], v[184:187], v[98:101]
	v_mfma_f32_16x16x32_bf16 v[86:89], v[146:149], v[202:205], v[86:89]
	v_mfma_f32_16x16x32_bf16 v[82:85], v[154:157], v[202:205], v[82:85]
	v_mfma_f32_16x16x32_bf16 v[70:73], v[146:149], v[210:213], v[70:73]
	v_mfma_f32_16x16x32_bf16 v[66:69], v[154:157], v[210:213], v[66:69]
	v_mfma_f32_16x16x32_bf16 v[118:121], v[150:153], v[180:183], v[118:121]
	v_mfma_f32_16x16x32_bf16 v[114:117], v[162:165], v[180:183], v[114:117]
	v_mfma_f32_16x16x32_bf16 v[102:105], v[150:153], v[188:191], v[102:105]
	v_mfma_f32_16x16x32_bf16 v[98:101], v[162:165], v[188:191], v[98:101]
	v_mfma_f32_16x16x32_bf16 v[86:89], v[150:153], v[206:209], v[86:89]
	v_mfma_f32_16x16x32_bf16 v[82:85], v[162:165], v[206:209], v[82:85]
	v_mfma_f32_16x16x32_bf16 v[70:73], v[150:153], v[214:217], v[70:73]
	v_mfma_f32_16x16x32_bf16 v[66:69], v[162:165], v[214:217], v[66:69]
	s_setprio 0
	s_barrier
	s_add_i32 s68, s68, s50
	s_mov_b32 m0, s68
	ds_read_b128 v[176:179], v201 offset:16384
	ds_read_b128 v[180:183], v201 offset:17408
	ds_read_b128 v[184:187], v201 offset:18432
	ds_read_b128 v[188:191], v201 offset:19456
	ds_read_b128 v[202:205], v201 offset:20480
	ds_read_b128 v[206:209], v201 offset:21504
	ds_read_b128 v[210:213], v201 offset:22528
	ds_read_b128 v[214:217], v201 offset:23552
	global_load_lds_dwordx4 v158, s[30:31]
	s_add_i32 m0, s68, 0x2000
	s_add_u32 s68, s30, 0x200000
	s_addc_u32 s69, s31, 0
	s_add_i32 s70, s70, s50
	global_load_lds_dwordx4 v166, s[30:31]
	s_mov_b32 m0, s70
	s_nop 0
	global_load_lds_dwordx4 v158, s[68:69]
	s_add_i32 m0, s70, 0x2000
	s_nop 0
	global_load_lds_dwordx4 v166, s[68:69]
	s_waitcnt vmcnt(6)
	s_waitcnt lgkmcnt(0)
	s_barrier
	s_setprio 1
	s_waitcnt lgkmcnt(0)
	v_mfma_f32_16x16x32_bf16 v[62:65], v[130:133], v[176:179], v[62:65]
	v_mfma_f32_16x16x32_bf16 v[58:61], v[138:141], v[176:179], v[58:61]
	v_mfma_f32_16x16x32_bf16 v[46:49], v[130:133], v[184:187], v[46:49]
	v_mfma_f32_16x16x32_bf16 v[42:45], v[138:141], v[184:187], v[42:45]
	v_mfma_f32_16x16x32_bf16 v[30:33], v[130:133], v[202:205], v[30:33]
	v_mfma_f32_16x16x32_bf16 v[26:29], v[138:141], v[202:205], v[26:29]
	v_mfma_f32_16x16x32_bf16 v[14:17], v[130:133], v[210:213], v[14:17]
	v_mfma_f32_16x16x32_bf16 v[10:13], v[138:141], v[210:213], v[10:13]
	v_mfma_f32_16x16x32_bf16 v[62:65], v[134:137], v[180:183], v[62:65]
	v_mfma_f32_16x16x32_bf16 v[58:61], v[142:145], v[180:183], v[58:61]
	v_mfma_f32_16x16x32_bf16 v[46:49], v[134:137], v[188:191], v[46:49]
	v_mfma_f32_16x16x32_bf16 v[42:45], v[142:145], v[188:191], v[42:45]
	v_mfma_f32_16x16x32_bf16 v[30:33], v[134:137], v[206:209], v[30:33]
	v_mfma_f32_16x16x32_bf16 v[26:29], v[142:145], v[206:209], v[26:29]
	v_mfma_f32_16x16x32_bf16 v[14:17], v[134:137], v[214:217], v[14:17]
	v_mfma_f32_16x16x32_bf16 v[10:13], v[142:145], v[214:217], v[10:13]
	s_setprio 0
	s_setprio 1
	v_mfma_f32_16x16x32_bf16 v[54:57], v[146:149], v[176:179], v[54:57]
	v_mfma_f32_16x16x32_bf16 v[50:53], v[154:157], v[176:179], v[50:53]
	v_mfma_f32_16x16x32_bf16 v[38:41], v[146:149], v[184:187], v[38:41]
	v_mfma_f32_16x16x32_bf16 v[34:37], v[154:157], v[184:187], v[34:37]
	v_mfma_f32_16x16x32_bf16 v[22:25], v[146:149], v[202:205], v[22:25]
	v_mfma_f32_16x16x32_bf16 v[18:21], v[154:157], v[202:205], v[18:21]
	v_mfma_f32_16x16x32_bf16 v[6:9], v[146:149], v[210:213], v[6:9]
	v_mfma_f32_16x16x32_bf16 v[2:5], v[154:157], v[210:213], v[2:5]
	v_mfma_f32_16x16x32_bf16 v[54:57], v[150:153], v[180:183], v[54:57]
	v_mfma_f32_16x16x32_bf16 v[50:53], v[162:165], v[180:183], v[50:53]
	v_mfma_f32_16x16x32_bf16 v[38:41], v[150:153], v[188:191], v[38:41]
	v_mfma_f32_16x16x32_bf16 v[34:37], v[162:165], v[188:191], v[34:37]
	v_mfma_f32_16x16x32_bf16 v[22:25], v[150:153], v[206:209], v[22:25]
	v_mfma_f32_16x16x32_bf16 v[18:21], v[162:165], v[206:209], v[18:21]
	v_mfma_f32_16x16x32_bf16 v[6:9], v[150:153], v[214:217], v[6:9]
	v_mfma_f32_16x16x32_bf16 v[2:5], v[162:165], v[214:217], v[2:5]
	s_setprio 0
	s_barrier
; #define PG8_STAGE(bufoff, gbase, voff) do { _Pragma("unroll") for (int _i = 0; _i < 2; ++_i) \
;         __builtin_amdgcn_global_load_lds((const unsigned*)((const char*)(gbase) + (voff)[_i]), (PG8_LAS unsigned*)(lds + (bufoff) + ldsw + _i * 8192), 16, 0, 0); } while (0)
; #define PG8_LDA(dst, b, h) do { _Pragma("unroll") for (int m = 0; m < 4; ++m) _Pragma("unroll") for (int k = 0; k < 2; ++k) dst[m][k] = *(const PG8_LAS bf16x8*)(lds + PG8_SA(b, h) + aoff + m * 2048 + k * 1024); } while (0)
; #define PG8_LDB(dst, b, h) do { _Pragma("unroll") for (int n = 0; n < 2; ++n) _Pragma("unroll") for (int k = 0; k < 2; ++k) dst[n][k] = *(const PG8_LAS bf16x8*)(lds + PG8_SB(b, h) + boff + n * 2048 + k * 1024); } while (0)
; #define PG8_MMA(ai, bj, At, Bt) do { __builtin_amdgcn_s_setprio(1); _Pragma("unroll") for (int m = 0; m < 4; ++m) _Pragma("unroll") for (int n = 0; n < 2; ++n) _Pragma("unroll") for (int k = 0; k < 2; ++k) \
;         acc[ai][bj][m][n] = __builtin_amdgcn_mfma_f32_16x16x32_bf16(Bt[n][k], At[m][k], acc[ai][bj][m][n], 0, 0, 0); __builtin_amdgcn_s_setprio(0); } while (0)
; #define PG8_WAIT_V(n) asm volatile("s_waitcnt vmcnt(" #n ")" ::: "memory")
; template <class Epi, class Sched, bool ALIGN_EPI = false, bool SP2 = false>
; __device__ __forceinline__ void gemm_phase(PG8_LAS unsigned char* lds, const Gemm g, const Sched& S, const Epi& E) {
;     ...
;             PG8_LDB(B0, 0, 0); PG8_LDB(B1, 0, 1); PG8_SCHED; PG8_LDA(At, 0, 0); PG8_STAGE(PG8_SA(1, 1), a1 + hstep, voffA);
;             PG8_WAIT_V(8); PG8_WAIT_L(0); PG8_BAR; PG8_MMA(0, 0, At, B0); PG8_MMA(0, 1, At, B1); PG8_BAR; PG8_SCHED;
;             PG8_LDA(At, 0, 1); PG8_STAGE(PG8_SB(0, 0), b2, voffB); PG8_STAGE(PG8_SB(0, 1), b2 + hstep, voffB); PG8_STAGE(PG8_SA(0, 0), a2, voffA);
;             PG8_WAIT_V(8); PG8_WAIT_L(0); PG8_BAR; PG8_MMA(1, 0, At, B0); PG8_MMA(1, 1, At, B1); PG8_BAR; PG8_SCHED;
;             PG8_LDB(B0, 1, 0); PG8_LDB(B1, 1, 1); PG8_SCHED; PG8_LDA(At, 1, 0); PG8_STAGE(PG8_SA(0, 1), a2 + hstep, voffA);
;             PG8_WAIT_V(8); PG8_WAIT_L(0); PG8_BAR; PG8_MMA(0, 0, At, B0); PG8_MMA(0, 1, At, B1); PG8_BAR; PG8_SCHED;
;             PG8_LDA(At, 1, 1); PG8_STAGE(PG8_SB(1, 0), b3, voffB); PG8_STAGE(PG8_SB(1, 1), b3 + hstep, voffB); PG8_STAGE(PG8_SA(1, 0), a3, voffA);
;             PG8_WAIT_V(8); PG8_WAIT_L(0); PG8_BAR; PG8_MMA(1, 0, At, B0); PG8_MMA(1, 1, At, B1); PG8_BAR; PG8_SCHED;
	s_add_i32 s68, 0, 0x18000
	s_add_i32 s69, 0, 0x1c000
	v_add_u32_e32 v142, s68, v199
	v_add_u32_e32 v162, s69, v199
	ds_read_b128 v[130:133], v142
	ds_read_b128 v[134:137], v142 offset:1024
	ds_read_b128 v[138:141], v142 offset:2048
	ds_read_b128 v[142:145], v142 offset:3072
	ds_read_b128 v[146:149], v162
	ds_read_b128 v[150:153], v162 offset:1024
	ds_read_b128 v[154:157], v162 offset:2048
	ds_read_b128 v[162:165], v162 offset:3072
	s_mov_b32 m0, s51
	s_nop 0
	global_load_lds_dwordx4 v170, s[36:37]
	s_mov_b32 m0, s52
	s_nop 0
	global_load_lds_dwordx4 v168, s[36:37]
	s_add_u32 s36, s36, 0x200000
	s_addc_u32 s37, s37, 0
	s_mov_b32 m0, s53
	ds_read_b128 v[176:179], v201 offset:32768
	ds_read_b128 v[180:183], v201 offset:33792
	ds_read_b128 v[184:187], v201 offset:34816
	ds_read_b128 v[188:191], v201 offset:35840
	ds_read_b128 v[202:205], v201 offset:36864
	ds_read_b128 v[206:209], v201 offset:37888
	ds_read_b128 v[210:213], v201 offset:38912
	ds_read_b128 v[214:217], v201 offset:39936
	global_load_lds_dwordx4 v170, s[36:37]
	s_mov_b32 m0, s54
	s_nop 0
	global_load_lds_dwordx4 v168, s[36:37]
	s_waitcnt vmcnt(8)
	s_waitcnt lgkmcnt(0)
	s_barrier
	s_setprio 1
	s_waitcnt lgkmcnt(0)
	v_mfma_f32_16x16x32_bf16 v[126:129], v[130:133], v[176:179], v[126:129]
	v_mfma_f32_16x16x32_bf16 v[122:125], v[138:141], v[176:179], v[122:125]
	v_mfma_f32_16x16x32_bf16 v[110:113], v[130:133], v[184:187], v[110:113]
	v_mfma_f32_16x16x32_bf16 v[106:109], v[138:141], v[184:187], v[106:109]
	v_mfma_f32_16x16x32_bf16 v[94:97], v[130:133], v[202:205], v[94:97]
	v_mfma_f32_16x16x32_bf16 v[90:93], v[138:141], v[202:205], v[90:93]
	v_mfma_f32_16x16x32_bf16 v[78:81], v[130:133], v[210:213], v[78:81]
	v_mfma_f32_16x16x32_bf16 v[74:77], v[138:141], v[210:213], v[74:77]
	v_mfma_f32_16x16x32_bf16 v[126:129], v[134:137], v[180:183], v[126:129]
	v_mfma_f32_16x16x32_bf16 v[122:125], v[142:145], v[180:183], v[122:125]
	v_mfma_f32_16x16x32_bf16 v[110:113], v[134:137], v[188:191], v[110:113]
	v_mfma_f32_16x16x32_bf16 v[106:109], v[142:145], v[188:191], v[106:109]
	v_mfma_f32_16x16x32_bf16 v[94:97], v[134:137], v[206:209], v[94:97]
	v_mfma_f32_16x16x32_bf16 v[90:93], v[142:145], v[206:209], v[90:93]
	v_mfma_f32_16x16x32_bf16 v[78:81], v[134:137], v[214:217], v[78:81]
	v_mfma_f32_16x16x32_bf16 v[74:77], v[142:145], v[214:217], v[74:77]
	s_setprio 0
	s_setprio 1
	v_mfma_f32_16x16x32_bf16 v[118:121], v[146:149], v[176:179], v[118:121]
	v_mfma_f32_16x16x32_bf16 v[114:117], v[154:157], v[176:179], v[114:117]
	v_mfma_f32_16x16x32_bf16 v[102:105], v[146:149], v[184:187], v[102:105]
	v_mfma_f32_16x16x32_bf16 v[98:101], v[154:157], v[184:187], v[98:101]
	v_mfma_f32_16x16x32_bf16 v[86:89], v[146:149], v[202:205], v[86:89]
	v_mfma_f32_16x16x32_bf16 v[82:85], v[154:157], v[202:205], v[82:85]
	v_mfma_f32_16x16x32_bf16 v[70:73], v[146:149], v[210:213], v[70:73]
	v_mfma_f32_16x16x32_bf16 v[66:69], v[154:157], v[210:213], v[66:69]
	v_mfma_f32_16x16x32_bf16 v[118:121], v[150:153], v[180:183], v[118:121]
	v_mfma_f32_16x16x32_bf16 v[114:117], v[162:165], v[180:183], v[114:117]
	v_mfma_f32_16x16x32_bf16 v[102:105], v[150:153], v[188:191], v[102:105]
	v_mfma_f32_16x16x32_bf16 v[98:101], v[162:165], v[188:191], v[98:101]
	v_mfma_f32_16x16x32_bf16 v[86:89], v[150:153], v[206:209], v[86:89]
	v_mfma_f32_16x16x32_bf16 v[82:85], v[162:165], v[206:209], v[82:85]
	v_mfma_f32_16x16x32_bf16 v[70:73], v[150:153], v[214:217], v[70:73]
	v_mfma_f32_16x16x32_bf16 v[66:69], v[162:165], v[214:217], v[66:69]
	s_setprio 0
	s_barrier
	s_add_i32 s36, s68, s50
	s_add_i32 m0, s36, 0xffffff80
	ds_read_b128 v[176:179], v201 offset:49152
	ds_read_b128 v[180:183], v201 offset:50176
	ds_read_b128 v[184:187], v201 offset:51200
	ds_read_b128 v[188:191], v201 offset:52224
	ds_read_b128 v[202:205], v201 offset:53248
	ds_read_b128 v[206:209], v201 offset:54272
	ds_read_b128 v[210:213], v201 offset:55296
	ds_read_b128 v[214:217], v201 offset:56320
	global_load_lds_dwordx4 v158, s[30:31] offset:128
	s_add_i32 m0, s36, 0x1f80
	s_add_i32 s36, s69, s50
	global_load_lds_dwordx4 v166, s[30:31] offset:128
	s_add_u32 s30, s30, 0x200080
	s_addc_u32 s31, s31, 0
	s_mov_b32 m0, s36
	s_nop 0
	global_load_lds_dwordx4 v158, s[30:31]
	s_add_i32 m0, s36, 0x2000
	s_nop 0
	global_load_lds_dwordx4 v166, s[30:31]
	s_waitcnt vmcnt(6)
	s_waitcnt lgkmcnt(0)
	s_barrier
	s_setprio 1
	s_waitcnt lgkmcnt(0)
	v_mfma_f32_16x16x32_bf16 v[62:65], v[130:133], v[176:179], v[62:65]
	v_mfma_f32_16x16x32_bf16 v[58:61], v[138:141], v[176:179], v[58:61]
	v_mfma_f32_16x16x32_bf16 v[46:49], v[130:133], v[184:187], v[46:49]
	v_mfma_f32_16x16x32_bf16 v[42:45], v[138:141], v[184:187], v[42:45]
	v_mfma_f32_16x16x32_bf16 v[30:33], v[130:133], v[202:205], v[30:33]
	v_mfma_f32_16x16x32_bf16 v[26:29], v[138:141], v[202:205], v[26:29]
	v_mfma_f32_16x16x32_bf16 v[14:17], v[130:133], v[210:213], v[14:17]
	v_mfma_f32_16x16x32_bf16 v[10:13], v[138:141], v[210:213], v[10:13]
	v_mfma_f32_16x16x32_bf16 v[62:65], v[134:137], v[180:183], v[62:65]
	v_mfma_f32_16x16x32_bf16 v[58:61], v[142:145], v[180:183], v[58:61]
	v_mfma_f32_16x16x32_bf16 v[46:49], v[134:137], v[188:191], v[46:49]
	v_mfma_f32_16x16x32_bf16 v[42:45], v[142:145], v[188:191], v[42:45]
	v_mfma_f32_16x16x32_bf16 v[30:33], v[134:137], v[206:209], v[30:33]
	v_mfma_f32_16x16x32_bf16 v[26:29], v[142:145], v[206:209], v[26:29]
	v_mfma_f32_16x16x32_bf16 v[14:17], v[134:137], v[214:217], v[14:17]
	v_mfma_f32_16x16x32_bf16 v[10:13], v[142:145], v[214:217], v[10:13]
	s_setprio 0
	s_setprio 1
	v_mfma_f32_16x16x32_bf16 v[54:57], v[146:149], v[176:179], v[54:57]
	v_mfma_f32_16x16x32_bf16 v[50:53], v[154:157], v[176:179], v[50:53]
	v_mfma_f32_16x16x32_bf16 v[38:41], v[146:149], v[184:187], v[38:41]
	v_mfma_f32_16x16x32_bf16 v[34:37], v[154:157], v[184:187], v[34:37]
	v_mfma_f32_16x16x32_bf16 v[22:25], v[146:149], v[202:205], v[22:25]
	v_mfma_f32_16x16x32_bf16 v[18:21], v[154:157], v[202:205], v[18:21]
	v_mfma_f32_16x16x32_bf16 v[6:9], v[146:149], v[210:213], v[6:9]
	v_mfma_f32_16x16x32_bf16 v[2:5], v[154:157], v[210:213], v[2:5]
	v_mfma_f32_16x16x32_bf16 v[54:57], v[150:153], v[180:183], v[54:57]
	v_mfma_f32_16x16x32_bf16 v[50:53], v[162:165], v[180:183], v[50:53]
	v_mfma_f32_16x16x32_bf16 v[38:41], v[150:153], v[188:191], v[38:41]
	v_mfma_f32_16x16x32_bf16 v[34:37], v[162:165], v[188:191], v[34:37]
	v_mfma_f32_16x16x32_bf16 v[22:25], v[150:153], v[206:209], v[22:25]
	v_mfma_f32_16x16x32_bf16 v[18:21], v[162:165], v[206:209], v[18:21]
	v_mfma_f32_16x16x32_bf16 v[6:9], v[150:153], v[214:217], v[6:9]
	v_mfma_f32_16x16x32_bf16 v[2:5], v[162:165], v[214:217], v[2:5]
	s_setprio 0
	s_barrier
	s_add_i32 s67, s67, 2
	s_add_u32 s0, s0, 0x100
	s_addc_u32 s1, s1, 0
	s_add_u32 s63, s63, 0x100
	s_addc_u32 s66, s66, 0
	s_cmpk_gt_u32 s67, 0x7d
	s_cbranch_scc0 .LBB0_842
	s_and_b64 vcc, exec, s[16:17]
	s_cbranch_vccz .LBB0_845
	s_barrier

; #define PG8_STAGE(bufoff, gbase, voff) do { _Pragma("unroll") for (int _i = 0; _i < 2; ++_i) \
;         __builtin_amdgcn_global_load_lds((const unsigned*)((const char*)(gbase) + (voff)[_i]), (PG8_LAS unsigned*)(lds + (bufoff) + ldsw + _i * 8192), 16, 0, 0); } while (0)
; #define PG8_LDA(dst, b, h) do { _Pragma("unroll") for (int m = 0; m < 4; ++m) _Pragma("unroll") for (int k = 0; k < 2; ++k) dst[m][k] = *(const PG8_LAS bf16x8*)(lds + PG8_SA(b, h) + aoff + m * 2048 + k * 1024); } while (0)
; #define PG8_LDB(dst, b, h) do { _Pragma("unroll") for (int n = 0; n < 2; ++n) _Pragma("unroll") for (int k = 0; k < 2; ++k) dst[n][k] = *(const PG8_LAS bf16x8*)(lds + PG8_SB(b, h) + boff + n * 2048 + k * 1024); } while (0)
; #define PG8_MMA(ai, bj, At, Bt) do { __builtin_amdgcn_s_setprio(1); _Pragma("unroll") for (int m = 0; m < 4; ++m) _Pragma("unroll") for (int n = 0; n < 2; ++n) _Pragma("unroll") for (int k = 0; k < 2; ++k) \
;         acc[ai][bj][m][n] = __builtin_amdgcn_mfma_f32_16x16x32_bf16(Bt[n][k], At[m][k], acc[ai][bj][m][n], 0, 0, 0); __builtin_amdgcn_s_setprio(0); } while (0)
; #define PG8_WAIT_V(n) asm volatile("s_waitcnt vmcnt(" #n ")" ::: "memory")
; template <class Epi, class Sched, bool ALIGN_EPI = false, bool SP2 = false>
; __device__ __forceinline__ void gemm_phase(PG8_LAS unsigned char* lds, const Gemm g, const Sched& S, const Epi& E) {
;     ...
;             PG8_LDB(B0, 0, 0); PG8_LDB(B1, 0, 1); PG8_SCHED; PG8_LDA(At, 0, 0); PG8_STAGE(PG8_SA(1, 1), a1 + hstep, voffA);
;             PG8_WAIT_V(8); PG8_WAIT_L(0); PG8_BAR; PG8_MMA(0, 0, At, B0); PG8_MMA(0, 1, At, B1); PG8_BAR; PG8_SCHED;
;             PG8_LDA(At, 0, 1); PG8_STAGE(PG8_SB(0, 0), b2, voffB); PG8_STAGE(PG8_SB(0, 1), b2 + hstep, voffB); PG8_STAGE(PG8_SA(0, 0), a2, voffA);
;             PG8_WAIT_V(8); PG8_WAIT_L(0); PG8_BAR; PG8_MMA(1, 0, At, B0); PG8_MMA(1, 1, At, B1); PG8_BAR; PG8_SCHED;
;             PG8_LDB(B0, 1, 0); PG8_LDB(B1, 1, 1); PG8_SCHED; PG8_LDA(At, 1, 0); PG8_STAGE(PG8_SA(0, 1), a2 + hstep, voffA);
;             PG8_WAIT_V(8); PG8_WAIT_L(0); PG8_BAR; PG8_MMA(0, 0, At, B0); PG8_MMA(0, 1, At, B1); PG8_BAR; PG8_SCHED;
;             PG8_LDA(At, 1, 1); PG8_STAGE(PG8_SB(1, 0), b3, voffB); PG8_STAGE(PG8_SB(1, 1), b3 + hstep, voffB); PG8_STAGE(PG8_SA(1, 0), a3, voffA);
;             PG8_WAIT_V(8); PG8_WAIT_L(0); PG8_BAR; PG8_MMA(1, 0, At, B0); PG8_MMA(1, 1, At, B1); PG8_BAR; PG8_SCHED;
.LBB0_880:
	s_add_u32 s28, s0, 0xffe00080
	s_addc_u32 s29, s1, -1
	s_add_i32 s59, 0, 0x10000
	s_cmpk_eq_i32 s58, 0x7c
	s_cselect_b32 s31, s19, s29
	s_cselect_b32 s30, s54, s28
	s_cselect_b32 s29, s17, s57
	s_cselect_b32 s28, s55, s56
	s_add_i32 s62, 0, 0x14000
	v_add_u32_e32 v142, s59, v178
	v_add_u32_e32 v172, s62, v178
	ds_read_b128 v[130:133], v142
	ds_read_b128 v[134:137], v142 offset:1024
	ds_read_b128 v[138:141], v142 offset:2048
	ds_read_b128 v[142:145], v142 offset:3072
	ds_read_b128 v[146:149], v172
	ds_read_b128 v[162:165], v172 offset:1024
	ds_read_b128 v[168:171], v172 offset:2048
	ds_read_b128 v[172:175], v172 offset:3072
	s_add_u32 s98, s0, 0xffe00000
	s_addc_u32 s99, s1, -1
	s_mov_b32 m0, s44
	s_nop 0
	global_load_lds_dwordx4 v156, s[98:99]
	s_mov_b32 m0, s45
	s_nop 0
	global_load_lds_dwordx4 v166, s[98:99]
	s_add_i32 m0, s36, 0xc000
	ds_read_b128 v[182:185], v180
	ds_read_b128 v[186:189], v180 offset:1024
	ds_read_b128 v[190:193], v180 offset:2048
	ds_read_b128 v[200:203], v180 offset:3072
	ds_read_b128 v[204:207], v180 offset:4096
	ds_read_b128 v[208:211], v180 offset:5120
	ds_read_b128 v[212:215], v180 offset:6144
	ds_read_b128 v[216:219], v180 offset:7168
	global_load_lds_dwordx4 v156, s[0:1]
	s_add_i32 m0, s36, 0xe000
	s_nop 0
	global_load_lds_dwordx4 v166, s[0:1]
	s_waitcnt vmcnt(8)
	s_waitcnt lgkmcnt(0)
	s_barrier
	s_setprio 1
	s_waitcnt lgkmcnt(0)
	v_mfma_f32_16x16x32_bf16 v[126:129], v[130:133], v[182:185], v[126:129]
	v_mfma_f32_16x16x32_bf16 v[122:125], v[138:141], v[182:185], v[122:125]
	v_mfma_f32_16x16x32_bf16 v[118:121], v[130:133], v[190:193], v[118:121]
	v_mfma_f32_16x16x32_bf16 v[114:117], v[138:141], v[190:193], v[114:117]
	v_mfma_f32_16x16x32_bf16 v[94:97], v[130:133], v[204:207], v[94:97]
	v_mfma_f32_16x16x32_bf16 v[90:93], v[138:141], v[204:207], v[90:93]
	v_mfma_f32_16x16x32_bf16 v[82:85], v[130:133], v[212:215], v[82:85]
	v_mfma_f32_16x16x32_bf16 v[74:77], v[138:141], v[212:215], v[74:77]
	v_mfma_f32_16x16x32_bf16 v[126:129], v[134:137], v[186:189], v[126:129]
	v_mfma_f32_16x16x32_bf16 v[122:125], v[142:145], v[186:189], v[122:125]
	v_mfma_f32_16x16x32_bf16 v[118:121], v[134:137], v[200:203], v[118:121]
	v_mfma_f32_16x16x32_bf16 v[114:117], v[142:145], v[200:203], v[114:117]
	v_mfma_f32_16x16x32_bf16 v[94:97], v[134:137], v[208:211], v[94:97]
	v_mfma_f32_16x16x32_bf16 v[90:93], v[142:145], v[208:211], v[90:93]
	v_mfma_f32_16x16x32_bf16 v[82:85], v[134:137], v[216:219], v[82:85]
	v_mfma_f32_16x16x32_bf16 v[74:77], v[142:145], v[216:219], v[74:77]
	s_setprio 0
	s_setprio 1
	v_mfma_f32_16x16x32_bf16 v[110:113], v[146:149], v[182:185], v[110:113]
	v_mfma_f32_16x16x32_bf16 v[106:109], v[168:171], v[182:185], v[106:109]
	v_mfma_f32_16x16x32_bf16 v[102:105], v[146:149], v[190:193], v[102:105]
	v_mfma_f32_16x16x32_bf16 v[98:101], v[168:171], v[190:193], v[98:101]
	v_mfma_f32_16x16x32_bf16 v[86:89], v[146:149], v[204:207], v[86:89]
	v_mfma_f32_16x16x32_bf16 v[78:81], v[168:171], v[204:207], v[78:81]
	v_mfma_f32_16x16x32_bf16 v[70:73], v[146:149], v[212:215], v[70:73]
	v_mfma_f32_16x16x32_bf16 v[66:69], v[168:171], v[212:215], v[66:69]
	v_mfma_f32_16x16x32_bf16 v[110:113], v[162:165], v[186:189], v[110:113]
	v_mfma_f32_16x16x32_bf16 v[106:109], v[172:175], v[186:189], v[106:109]
	v_mfma_f32_16x16x32_bf16 v[102:105], v[162:165], v[200:203], v[102:105]
	v_mfma_f32_16x16x32_bf16 v[98:101], v[172:175], v[200:203], v[98:101]
	v_mfma_f32_16x16x32_bf16 v[86:89], v[162:165], v[208:211], v[86:89]
	v_mfma_f32_16x16x32_bf16 v[78:81], v[172:175], v[208:211], v[78:81]
	v_mfma_f32_16x16x32_bf16 v[70:73], v[162:165], v[216:219], v[70:73]
	v_mfma_f32_16x16x32_bf16 v[66:69], v[172:175], v[216:219], v[66:69]
	s_setprio 0
	s_barrier
	s_add_i32 s59, s59, s34
	s_mov_b32 m0, s59
	ds_read_b128 v[182:185], v180 offset:16384
	ds_read_b128 v[186:189], v180 offset:17408
	ds_read_b128 v[190:193], v180 offset:18432
	ds_read_b128 v[200:203], v180 offset:19456
	ds_read_b128 v[204:207], v180 offset:20480
	ds_read_b128 v[208:211], v180 offset:21504
	ds_read_b128 v[212:215], v180 offset:22528
	ds_read_b128 v[216:219], v180 offset:23552
	global_load_lds_dwordx4 v158, s[28:29]
	s_add_i32 m0, s59, 0x2000
	s_add_u32 s60, s28, 0x200000
	s_addc_u32 s61, s29, 0
	s_add_i32 s59, s62, s34
	global_load_lds_dwordx4 v150, s[28:29]
	s_mov_b32 m0, s59
	s_nop 0
	global_load_lds_dwordx4 v158, s[60:61]
	s_add_i32 m0, s59, 0x2000
	s_nop 0
	global_load_lds_dwordx4 v150, s[60:61]
	s_waitcnt vmcnt(6)
	s_waitcnt lgkmcnt(0)
	s_barrier
	s_setprio 1
	s_waitcnt lgkmcnt(0)
	v_mfma_f32_16x16x32_bf16 v[62:65], v[130:133], v[182:185], v[62:65]
	v_mfma_f32_16x16x32_bf16 v[58:61], v[138:141], v[182:185], v[58:61]
	v_mfma_f32_16x16x32_bf16 v[50:53], v[130:133], v[190:193], v[50:53]
	v_mfma_f32_16x16x32_bf16 v[42:45], v[138:141], v[190:193], v[42:45]
	v_mfma_f32_16x16x32_bf16 v[34:37], v[130:133], v[204:207], v[34:37]
	v_mfma_f32_16x16x32_bf16 v[26:29], v[138:141], v[204:207], v[26:29]
	v_mfma_f32_16x16x32_bf16 v[18:21], v[130:133], v[212:215], v[18:21]
	v_mfma_f32_16x16x32_bf16 v[10:13], v[138:141], v[212:215], v[10:13]
	v_mfma_f32_16x16x32_bf16 v[62:65], v[134:137], v[186:189], v[62:65]
	v_mfma_f32_16x16x32_bf16 v[58:61], v[142:145], v[186:189], v[58:61]
	v_mfma_f32_16x16x32_bf16 v[50:53], v[134:137], v[200:203], v[50:53]
	v_mfma_f32_16x16x32_bf16 v[42:45], v[142:145], v[200:203], v[42:45]
	v_mfma_f32_16x16x32_bf16 v[34:37], v[134:137], v[208:211], v[34:37]
	v_mfma_f32_16x16x32_bf16 v[26:29], v[142:145], v[208:211], v[26:29]
	v_mfma_f32_16x16x32_bf16 v[18:21], v[134:137], v[216:219], v[18:21]
	v_mfma_f32_16x16x32_bf16 v[10:13], v[142:145], v[216:219], v[10:13]
	s_setprio 0
	s_setprio 1
	v_mfma_f32_16x16x32_bf16 v[54:57], v[146:149], v[182:185], v[54:57]
	v_mfma_f32_16x16x32_bf16 v[46:49], v[168:171], v[182:185], v[46:49]
	v_mfma_f32_16x16x32_bf16 v[38:41], v[146:149], v[190:193], v[38:41]
	v_mfma_f32_16x16x32_bf16 v[30:33], v[168:171], v[190:193], v[30:33]
	v_mfma_f32_16x16x32_bf16 v[22:25], v[146:149], v[204:207], v[22:25]
	v_mfma_f32_16x16x32_bf16 v[14:17], v[168:171], v[204:207], v[14:17]
	v_mfma_f32_16x16x32_bf16 v[6:9], v[146:149], v[212:215], v[6:9]
	v_mfma_f32_16x16x32_bf16 v[2:5], v[168:171], v[212:215], v[2:5]
	v_mfma_f32_16x16x32_bf16 v[54:57], v[162:165], v[186:189], v[54:57]
	v_mfma_f32_16x16x32_bf16 v[46:49], v[172:175], v[186:189], v[46:49]
	v_mfma_f32_16x16x32_bf16 v[38:41], v[162:165], v[200:203], v[38:41]
	v_mfma_f32_16x16x32_bf16 v[30:33], v[172:175], v[200:203], v[30:33]
	v_mfma_f32_16x16x32_bf16 v[22:25], v[162:165], v[208:211], v[22:25]
	v_mfma_f32_16x16x32_bf16 v[14:17], v[172:175], v[208:211], v[14:17]
	v_mfma_f32_16x16x32_bf16 v[6:9], v[162:165], v[216:219], v[6:9]
	v_mfma_f32_16x16x32_bf16 v[2:5], v[172:175], v[216:219], v[2:5]
	s_setprio 0
	s_barrier
; #define PG8_STAGE(bufoff, gbase, voff) do { _Pragma("unroll") for (int _i = 0; _i < 2; ++_i) \
;         __builtin_amdgcn_global_load_lds((const unsigned*)((const char*)(gbase) + (voff)[_i]), (PG8_LAS unsigned*)(lds + (bufoff) + ldsw + _i * 8192), 16, 0, 0); } while (0)
; #define PG8_LDA(dst, b, h) do { _Pragma("unroll") for (int m = 0; m < 4; ++m) _Pragma("unroll") for (int k = 0; k < 2; ++k) dst[m][k] = *(const PG8_LAS bf16x8*)(lds + PG8_SA(b, h) + aoff + m * 2048 + k * 1024); } while (0)
; #define PG8_LDB(dst, b, h) do { _Pragma("unroll") for (int n = 0; n < 2; ++n) _Pragma("unroll") for (int k = 0; k < 2; ++k) dst[n][k] = *(const PG8_LAS bf16x8*)(lds + PG8_SB(b, h) + boff + n * 2048 + k * 1024); } while (0)
; #define PG8_MMA(ai, bj, At, Bt) do { __builtin_amdgcn_s_setprio(1); _Pragma("unroll") for (int m = 0; m < 4; ++m) _Pragma("unroll") for (int n = 0; n < 2; ++n) _Pragma("unroll") for (int k = 0; k < 2; ++k) \
;         acc[ai][bj][m][n] = __builtin_amdgcn_mfma_f32_16x16x32_bf16(Bt[n][k], At[m][k], acc[ai][bj][m][n], 0, 0, 0); __builtin_amdgcn_s_setprio(0); } while (0)
; #define PG8_WAIT_V(n) asm volatile("s_waitcnt vmcnt(" #n ")" ::: "memory")
; #define PG8_WAIT_L(n) asm volatile("s_waitcnt lgkmcnt(" #n ")" ::: "memory")
; #define PG8_BAR __builtin_amdgcn_s_barrier()
; #define PG8_SCHED __builtin_amdgcn_sched_barrier(0)
; template <class Epi, class Sched, bool ALIGN_EPI = false, bool SP2 = false>
; __device__ __forceinline__ void gemm_phase(PG8_LAS unsigned char* lds, const Gemm g, const Sched& S, const Epi& E) {
;     ...
;             PG8_LDB(B0, 1, 0); PG8_LDB(B1, 1, 1); PG8_SCHED; PG8_LDA(At, 1, 0); PG8_STAGE(PG8_SA(0, 1), a2 + hstep, voffA);
;             PG8_WAIT_V(8); PG8_WAIT_L(0); PG8_BAR; PG8_MMA(0, 0, At, B0); PG8_MMA(0, 1, At, B1); PG8_BAR; PG8_SCHED;
;             PG8_LDA(At, 1, 1); PG8_STAGE(PG8_SB(1, 0), b3, voffB); PG8_STAGE(PG8_SB(1, 1), b3 + hstep, voffB); PG8_STAGE(PG8_SA(1, 0), a3, voffA);
;             PG8_WAIT_V(8); PG8_WAIT_L(0); PG8_BAR; PG8_MMA(1, 0, At, B0); PG8_MMA(1, 1, At, B1); PG8_BAR; PG8_SCHED;
;     ...
;         if constexpr (ALIGN_EPI) { if (wr == 0) PG8_BAR; }
	s_add_i32 s59, 0, 0x18000
	s_add_i32 s60, 0, 0x1c000
	v_add_u32_e32 v142, s59, v178
	v_add_u32_e32 v172, s60, v178
	ds_read_b128 v[130:133], v142
	ds_read_b128 v[134:137], v142 offset:1024
	ds_read_b128 v[138:141], v142 offset:2048
	ds_read_b128 v[142:145], v142 offset:3072
	ds_read_b128 v[146:149], v172
	ds_read_b128 v[162:165], v172 offset:1024
	ds_read_b128 v[168:171], v172 offset:2048
	ds_read_b128 v[172:175], v172 offset:3072
	s_mov_b32 m0, s36
	s_nop 0
	global_load_lds_dwordx4 v154, s[30:31]
	s_mov_b32 m0, s37
	s_nop 0
	global_load_lds_dwordx4 v152, s[30:31]
	s_add_u32 s30, s30, 0x200000
	s_addc_u32 s31, s31, 0
	s_mov_b32 m0, s42
	ds_read_b128 v[182:185], v180 offset:32768
	ds_read_b128 v[186:189], v180 offset:33792
	ds_read_b128 v[190:193], v180 offset:34816
	ds_read_b128 v[200:203], v180 offset:35840
	ds_read_b128 v[204:207], v180 offset:36864
	ds_read_b128 v[208:211], v180 offset:37888
	ds_read_b128 v[212:215], v180 offset:38912
	ds_read_b128 v[216:219], v180 offset:39936
	global_load_lds_dwordx4 v154, s[30:31]
	s_mov_b32 m0, s43
	s_nop 0
	global_load_lds_dwordx4 v152, s[30:31]
	s_waitcnt vmcnt(8)
	s_waitcnt lgkmcnt(0)
	s_barrier
	s_setprio 1
	s_waitcnt lgkmcnt(0)
	v_mfma_f32_16x16x32_bf16 v[126:129], v[130:133], v[182:185], v[126:129]
	v_mfma_f32_16x16x32_bf16 v[122:125], v[138:141], v[182:185], v[122:125]
	v_mfma_f32_16x16x32_bf16 v[118:121], v[130:133], v[190:193], v[118:121]
	v_mfma_f32_16x16x32_bf16 v[114:117], v[138:141], v[190:193], v[114:117]
	v_mfma_f32_16x16x32_bf16 v[94:97], v[130:133], v[204:207], v[94:97]
	v_mfma_f32_16x16x32_bf16 v[90:93], v[138:141], v[204:207], v[90:93]
	v_mfma_f32_16x16x32_bf16 v[82:85], v[130:133], v[212:215], v[82:85]
	v_mfma_f32_16x16x32_bf16 v[74:77], v[138:141], v[212:215], v[74:77]
	v_mfma_f32_16x16x32_bf16 v[126:129], v[134:137], v[186:189], v[126:129]
	v_mfma_f32_16x16x32_bf16 v[122:125], v[142:145], v[186:189], v[122:125]
	v_mfma_f32_16x16x32_bf16 v[118:121], v[134:137], v[200:203], v[118:121]
	v_mfma_f32_16x16x32_bf16 v[114:117], v[142:145], v[200:203], v[114:117]
	v_mfma_f32_16x16x32_bf16 v[94:97], v[134:137], v[208:211], v[94:97]
	v_mfma_f32_16x16x32_bf16 v[90:93], v[142:145], v[208:211], v[90:93]
	v_mfma_f32_16x16x32_bf16 v[82:85], v[134:137], v[216:219], v[82:85]
	v_mfma_f32_16x16x32_bf16 v[74:77], v[142:145], v[216:219], v[74:77]
	s_setprio 0
	s_setprio 1
	v_mfma_f32_16x16x32_bf16 v[110:113], v[146:149], v[182:185], v[110:113]
	v_mfma_f32_16x16x32_bf16 v[106:109], v[168:171], v[182:185], v[106:109]
	v_mfma_f32_16x16x32_bf16 v[102:105], v[146:149], v[190:193], v[102:105]
	v_mfma_f32_16x16x32_bf16 v[98:101], v[168:171], v[190:193], v[98:101]
	v_mfma_f32_16x16x32_bf16 v[86:89], v[146:149], v[204:207], v[86:89]
	v_mfma_f32_16x16x32_bf16 v[78:81], v[168:171], v[204:207], v[78:81]
	v_mfma_f32_16x16x32_bf16 v[70:73], v[146:149], v[212:215], v[70:73]
	v_mfma_f32_16x16x32_bf16 v[66:69], v[168:171], v[212:215], v[66:69]
	v_mfma_f32_16x16x32_bf16 v[110:113], v[162:165], v[186:189], v[110:113]
	v_mfma_f32_16x16x32_bf16 v[106:109], v[172:175], v[186:189], v[106:109]
	v_mfma_f32_16x16x32_bf16 v[102:105], v[162:165], v[200:203], v[102:105]
	v_mfma_f32_16x16x32_bf16 v[98:101], v[172:175], v[200:203], v[98:101]
	v_mfma_f32_16x16x32_bf16 v[86:89], v[162:165], v[208:211], v[86:89]
	v_mfma_f32_16x16x32_bf16 v[78:81], v[172:175], v[208:211], v[78:81]
	v_mfma_f32_16x16x32_bf16 v[70:73], v[162:165], v[216:219], v[70:73]
	v_mfma_f32_16x16x32_bf16 v[66:69], v[172:175], v[216:219], v[66:69]
	s_setprio 0
	s_barrier
	s_add_i32 s30, s59, s34
	s_add_i32 m0, s30, 0xffffff80
	ds_read_b128 v[182:185], v180 offset:49152
	ds_read_b128 v[186:189], v180 offset:50176
	ds_read_b128 v[190:193], v180 offset:51200
	ds_read_b128 v[200:203], v180 offset:52224
	ds_read_b128 v[204:207], v180 offset:53248
	ds_read_b128 v[208:211], v180 offset:54272
	ds_read_b128 v[212:215], v180 offset:55296
	ds_read_b128 v[216:219], v180 offset:56320
	global_load_lds_dwordx4 v158, s[28:29] offset:128
	s_add_i32 m0, s30, 0x1f80
	s_add_i32 s30, s60, s34
	global_load_lds_dwordx4 v150, s[28:29] offset:128
	s_add_u32 s28, s28, 0x200080
	s_addc_u32 s29, s29, 0
	s_mov_b32 m0, s30
	s_nop 0
	global_load_lds_dwordx4 v158, s[28:29]
	s_add_i32 m0, s30, 0x2000
	s_nop 0
	global_load_lds_dwordx4 v150, s[28:29]
	s_waitcnt vmcnt(6)
	s_waitcnt lgkmcnt(0)
	s_barrier
	s_setprio 1
	s_waitcnt lgkmcnt(0)
	v_mfma_f32_16x16x32_bf16 v[62:65], v[130:133], v[182:185], v[62:65]
	v_mfma_f32_16x16x32_bf16 v[58:61], v[138:141], v[182:185], v[58:61]
	v_mfma_f32_16x16x32_bf16 v[50:53], v[130:133], v[190:193], v[50:53]
	v_mfma_f32_16x16x32_bf16 v[42:45], v[138:141], v[190:193], v[42:45]
	v_mfma_f32_16x16x32_bf16 v[34:37], v[130:133], v[204:207], v[34:37]
	v_mfma_f32_16x16x32_bf16 v[26:29], v[138:141], v[204:207], v[26:29]
	v_mfma_f32_16x16x32_bf16 v[18:21], v[130:133], v[212:215], v[18:21]
	v_mfma_f32_16x16x32_bf16 v[10:13], v[138:141], v[212:215], v[10:13]
	v_mfma_f32_16x16x32_bf16 v[62:65], v[134:137], v[186:189], v[62:65]
	v_mfma_f32_16x16x32_bf16 v[58:61], v[142:145], v[186:189], v[58:61]
	v_mfma_f32_16x16x32_bf16 v[50:53], v[134:137], v[200:203], v[50:53]
	v_mfma_f32_16x16x32_bf16 v[42:45], v[142:145], v[200:203], v[42:45]
	v_mfma_f32_16x16x32_bf16 v[34:37], v[134:137], v[208:211], v[34:37]
	v_mfma_f32_16x16x32_bf16 v[26:29], v[142:145], v[208:211], v[26:29]
	v_mfma_f32_16x16x32_bf16 v[18:21], v[134:137], v[216:219], v[18:21]
	v_mfma_f32_16x16x32_bf16 v[10:13], v[142:145], v[216:219], v[10:13]
	s_setprio 0
	s_setprio 1
	v_mfma_f32_16x16x32_bf16 v[54:57], v[146:149], v[182:185], v[54:57]
	v_mfma_f32_16x16x32_bf16 v[46:49], v[168:171], v[182:185], v[46:49]
	v_mfma_f32_16x16x32_bf16 v[38:41], v[146:149], v[190:193], v[38:41]
	v_mfma_f32_16x16x32_bf16 v[30:33], v[168:171], v[190:193], v[30:33]
	v_mfma_f32_16x16x32_bf16 v[22:25], v[146:149], v[204:207], v[22:25]
	v_mfma_f32_16x16x32_bf16 v[14:17], v[168:171], v[204:207], v[14:17]
	v_mfma_f32_16x16x32_bf16 v[6:9], v[146:149], v[212:215], v[6:9]
	v_mfma_f32_16x16x32_bf16 v[2:5], v[168:171], v[212:215], v[2:5]
	v_mfma_f32_16x16x32_bf16 v[54:57], v[162:165], v[186:189], v[54:57]
	v_mfma_f32_16x16x32_bf16 v[46:49], v[172:175], v[186:189], v[46:49]
	v_mfma_f32_16x16x32_bf16 v[38:41], v[162:165], v[200:203], v[38:41]
	v_mfma_f32_16x16x32_bf16 v[30:33], v[172:175], v[200:203], v[30:33]
	v_mfma_f32_16x16x32_bf16 v[22:25], v[162:165], v[208:211], v[22:25]
	v_mfma_f32_16x16x32_bf16 v[14:17], v[172:175], v[208:211], v[14:17]
	v_mfma_f32_16x16x32_bf16 v[6:9], v[162:165], v[216:219], v[6:9]
	v_mfma_f32_16x16x32_bf16 v[2:5], v[172:175], v[216:219], v[2:5]
	s_setprio 0
	s_barrier
	s_add_i32 s58, s58, 2
	s_add_u32 s0, s0, 0x100
	s_addc_u32 s1, s1, 0
	s_add_u32 s56, s56, 0x100
	s_addc_u32 s57, s57, 0
	s_cmpk_gt_u32 s58, 0x7d
	s_cbranch_scc0 .LBB0_880
	s_and_b64 vcc, exec, s[14:15]
	s_cbranch_vccz .LBB0_883
	s_barrier
